# GEMM tiles: accumulator zeroing (128 v_mov per tile) removed; first K-iteration peeled with zero accumulator input on each accumulator's first MFMA (5 of 6 GEMM phases); on top of v58
# speedup vs baseline: 1.0094x; 1.0013x over previous
;     DI bool next(int i, Unit& u) const { const long L = (long)i * G + c; if (L >= T.nwg) return false; T.map((int)L, u.pm, u.pn); u.seg = 0; return true; }
;     DI bool next(int i, Unit& u) const { const int ti = i / 3; const long L = (long)ti * G + c; if (L >= T.nwg) return false; T.map((int)L, u.pm, u.pn); u.seg = i - 3 * ti; return true; }
;     DI const char* aptr(const Unit& u) const { return A + (size_t)u.pm * ta + (size_t)kofs(u.seg) * 2; }
;     DI const char* bptr(const Unit& u) const { return B + (size_t)u.pn * tb + (size_t)kofs(u.seg) * 2; }
; #define PG8_STAGE(bufoff, gbase, voff) do { _Pragma("unroll") for (int _i = 0; _i < 2; ++_i) \
;         __builtin_amdgcn_global_load_lds((const unsigned*)((const char*)(gbase) + (voff)[_i]), (LAS unsigned*)(lds + (bufoff) + ldsw + _i * 8192), 16, 0, 0); } while (0)
; #define PG8_LDA(dst, b, h) do { _Pragma("unroll") for (int m = 0; m < 4; ++m) _Pragma("unroll") for (int k = 0; k < 2; ++k) dst[m][k] = *(const LAS bf16x8*)(lds + PG8_SA(b, h) + aoff + m * 2048 + k * 1024); } while (0)
; #define PG8_WAIT_V(n) asm volatile("s_waitcnt vmcnt(" #n ")" ::: "memory")
; #define PG8_WAIT_L(n) asm volatile("s_waitcnt lgkmcnt(" #n ")" ::: "memory")
; template <class Epi, class Sched>
; DI void gemm_phase(LAS unsigned char* lds, const int wv, const int lda, const int ldb, const Sched& S, const Epi& E) {
;     ...
;         const bool has_next = S.next(ui + 1, nxt);
;         const char* nA = has_next ? S.aptr(nxt) : cA; const char* nB = has_next ? S.bptr(nxt) : cB;
;         for (int t = 0; t < nt; t += 2) {
;             const bool last = (t == nt - 2);
;             const char* a1 = cA + (size_t)(t + 1) * kstep;
;             const char* a2 = last ? nA : cA + (size_t)(t + 2) * kstep; const char* b2 = last ? nB : cB + (size_t)(t + 2) * kstep;
;             const char* a3 = a2 + kstep; const char* b3 = b2 + kstep;
;             PG8_LDB(B0, 0, 0); PG8_LDB(B1, 0, 1); PG8_SCHED; PG8_LDA(At, 0, 0); PG8_STAGE(PG8_SA(1, 1), a1 + hstepA, voffA);
;             PG8_WAIT_V(8); PG8_WAIT_L(0); PG8_BAR; PG8_MMA(0, 0, At, B0); PG8_MMA(0, 1, At, B1); PG8_BAR; PG8_SCHED;
;             PG8_LDA(At, 0, 1); PG8_STAGE(PG8_SB(0, 0), b2, voffB); PG8_STAGE(PG8_SB(0, 1), b2 + hstepB, voffB); PG8_STAGE(PG8_SA(0, 0), a2, voffA);
;             PG8_WAIT_V(8); PG8_WAIT_L(0); PG8_BAR; PG8_MMA(1, 0, At, B0); PG8_MMA(1, 1, At, B1); PG8_BAR; PG8_SCHED;
.LBB0_377:
	s_ashr_i32 s23, s22, 31
	s_lshl_b64 s[0:1], s[22:23], 20
	s_add_u32 s24, s8, s0
	s_addc_u32 s25, s9, s1
	s_and_b64 s[0:1], s[40:41], exec
	s_cselect_b32 s0, s25, s35
	s_cselect_b32 s1, s24, s34
	s_ashr_i32 s19, s18, 31
	s_lshl_b64 s[16:17], s[18:19], 20
	s_add_u32 s26, s45, s16
	s_addc_u32 s27, s46, s17
	s_and_b64 s[16:17], s[40:41], exec
	s_cselect_b32 s5, s27, s37
	s_cselect_b32 s16, s26, s36
	s_add_u32 s34, s34, 0x80080
	s_addc_u32 s35, s35, 0
	s_add_u32 s17, s36, 0x100
	s_addc_u32 s19, s37, 0
	s_mov_b32 s23, -2
	s_waitcnt vmcnt(0)
	s_add_u32 s33, s34, 0xfff80080
	s_addc_u32 s36, s35, -1
	s_add_i32 s61, 0, 0x10000
	s_cmp_eq_u32 s23, 28
	s_cselect_b32 s39, s0, s36
	s_cselect_b32 s38, s1, s33
	s_cselect_b32 s37, s5, s19
	s_cselect_b32 s36, s16, s17
	s_add_i32 s33, 0, 0x14000
	v_add_u32_e32 v154, s61, v170
	v_add_u32_e32 v173, s33, v170
	ds_read_b128 v[104:107], v154
	ds_read_b128 v[108:111], v154 offset:1024
	ds_read_b128 v[150:153], v154 offset:2048
	ds_read_b128 v[154:157], v154 offset:3072
	ds_read_b128 v[158:161], v173
	ds_read_b128 v[162:165], v173 offset:1024
	ds_read_b128 v[166:169], v173 offset:2048
	ds_read_b128 v[174:177], v173 offset:3072
	v_lshl_add_u64 v[182:183], s[34:35], 0, v[146:147]
	s_add_i32 m0, s31, 0xc000
	ds_read_b128 v[178:181], v172
	ds_read_b128 v[200:203], v172 offset:1024
	ds_read_b128 v[204:207], v172 offset:2048
	ds_read_b128 v[208:211], v172 offset:3072
	ds_read_b128 v[212:215], v172 offset:4096
	ds_read_b128 v[216:219], v172 offset:5120
	ds_read_b128 v[220:223], v172 offset:6144
	ds_read_b128 v[234:237], v172 offset:7168
	global_load_lds_dwordx4 v[182:183], off
	v_lshl_add_u64 v[182:183], s[34:35], 0, v[148:149]
	s_add_i32 m0, s31, 0xe000
	s_nop 0
	global_load_lds_dwordx4 v[182:183], off
	s_waitcnt vmcnt(8) lgkmcnt(0)
	s_barrier
	v_mfma_f32_16x16x32_bf16 v[132:135], v[104:107], v[178:181], 0
	v_mfma_f32_16x16x32_bf16 v[128:131], v[150:153], v[178:181], 0
	v_mfma_f32_16x16x32_bf16 v[124:127], v[104:107], v[204:207], 0
	v_mfma_f32_16x16x32_bf16 v[120:123], v[150:153], v[204:207], 0
	v_mfma_f32_16x16x32_bf16 v[116:119], v[104:107], v[212:215], 0
	v_mfma_f32_16x16x32_bf16 v[112:115], v[150:153], v[212:215], 0
	v_mfma_f32_16x16x32_bf16 v[100:103], v[104:107], v[220:223], 0
	v_mfma_f32_16x16x32_bf16 v[96:99], v[150:153], v[220:223], 0
	v_mfma_f32_16x16x32_bf16 v[132:135], v[108:111], v[200:203], v[132:135]
	v_mfma_f32_16x16x32_bf16 v[128:131], v[154:157], v[200:203], v[128:131]
	v_mfma_f32_16x16x32_bf16 v[124:127], v[108:111], v[208:211], v[124:127]
	v_mfma_f32_16x16x32_bf16 v[120:123], v[154:157], v[208:211], v[120:123]
	v_mfma_f32_16x16x32_bf16 v[116:119], v[108:111], v[216:219], v[116:119]
	v_mfma_f32_16x16x32_bf16 v[112:115], v[154:157], v[216:219], v[112:115]
	v_mfma_f32_16x16x32_bf16 v[100:103], v[108:111], v[234:237], v[100:103]
	v_mfma_f32_16x16x32_bf16 v[96:99], v[154:157], v[234:237], v[96:99]
	v_mfma_f32_16x16x32_bf16 v[60:63], v[158:161], v[178:181], 0
	v_mfma_f32_16x16x32_bf16 v[56:59], v[166:169], v[178:181], 0
	v_mfma_f32_16x16x32_bf16 v[52:55], v[158:161], v[204:207], 0
	v_mfma_f32_16x16x32_bf16 v[48:51], v[166:169], v[204:207], 0
	v_mfma_f32_16x16x32_bf16 v[44:47], v[158:161], v[212:215], 0
	v_mfma_f32_16x16x32_bf16 v[40:43], v[166:169], v[212:215], 0
	v_mfma_f32_16x16x32_bf16 v[36:39], v[158:161], v[220:223], 0
	v_mfma_f32_16x16x32_bf16 v[32:35], v[166:169], v[220:223], 0
	v_mfma_f32_16x16x32_bf16 v[60:63], v[162:165], v[200:203], v[60:63]
	v_mfma_f32_16x16x32_bf16 v[56:59], v[174:177], v[200:203], v[56:59]
	v_mfma_f32_16x16x32_bf16 v[52:55], v[162:165], v[208:211], v[52:55]
	v_mfma_f32_16x16x32_bf16 v[48:51], v[174:177], v[208:211], v[48:51]
	v_mfma_f32_16x16x32_bf16 v[44:47], v[162:165], v[216:219], v[44:47]
	v_mfma_f32_16x16x32_bf16 v[40:43], v[174:177], v[216:219], v[40:43]
	v_mfma_f32_16x16x32_bf16 v[36:39], v[162:165], v[234:237], v[36:39]
	v_mfma_f32_16x16x32_bf16 v[32:35], v[174:177], v[234:237], v[32:35]
	s_barrier
	s_add_i32 s61, s61, s47
	v_lshl_add_u64 v[182:183], s[36:37], 0, v[138:139]
	s_mov_b32 m0, s61
	ds_read_b128 v[178:181], v172 offset:16384
	ds_read_b128 v[200:203], v172 offset:17408
	ds_read_b128 v[204:207], v172 offset:18432
	ds_read_b128 v[208:211], v172 offset:19456
	ds_read_b128 v[212:215], v172 offset:20480
	ds_read_b128 v[216:219], v172 offset:21504
	ds_read_b128 v[220:223], v172 offset:22528
	ds_read_b128 v[234:237], v172 offset:23552
	global_load_lds_dwordx4 v[182:183], off
	s_add_i32 m0, s61, 0x2000
	s_add_u32 s62, s36, 0x80000
	v_lshl_add_u64 v[188:189], s[36:37], 0, v[142:143]
	s_addc_u32 s63, s37, 0
	s_add_i32 s33, s33, s47
	global_load_lds_dwordx4 v[188:189], off
	v_lshl_add_u64 v[190:191], s[62:63], 0, v[138:139]
	s_mov_b32 m0, s33
	v_lshl_add_u64 v[196:197], s[38:39], 0, v[140:141]
	global_load_lds_dwordx4 v[190:191], off
	v_lshl_add_u64 v[190:191], s[62:63], 0, v[142:143]
	s_add_i32 m0, s33, 0x2000
	s_nop 0
	global_load_lds_dwordx4 v[190:191], off
	v_lshl_add_u64 v[190:191], s[38:39], 0, v[136:137]
	s_mov_b32 m0, s31
	s_nop 0
	global_load_lds_dwordx4 v[190:191], off
	s_mov_b32 m0, s48
	s_nop 0
	global_load_lds_dwordx4 v[196:197], off
	s_waitcnt vmcnt(8) lgkmcnt(0)
	s_barrier
; #define PG8_STAGE(bufoff, gbase, voff) do { _Pragma("unroll") for (int _i = 0; _i < 2; ++_i) \
;         __builtin_amdgcn_global_load_lds((const unsigned*)((const char*)(gbase) + (voff)[_i]), (LAS unsigned*)(lds + (bufoff) + ldsw + _i * 8192), 16, 0, 0); } while (0)
; #define PG8_LDA(dst, b, h) do { _Pragma("unroll") for (int m = 0; m < 4; ++m) _Pragma("unroll") for (int k = 0; k < 2; ++k) dst[m][k] = *(const LAS bf16x8*)(lds + PG8_SA(b, h) + aoff + m * 2048 + k * 1024); } while (0)
; #define PG8_LDB(dst, b, h) do { _Pragma("unroll") for (int n = 0; n < 2; ++n) _Pragma("unroll") for (int k = 0; k < 2; ++k) dst[n][k] = *(const LAS bf16x8*)(lds + PG8_SB(b, h) + boff + n * 2048 + k * 1024); } while (0)
; #define PG8_MMA(ai, bj, At, Bt) do { __builtin_amdgcn_s_setprio(1); _Pragma("unroll") for (int m = 0; m < 4; ++m) _Pragma("unroll") for (int n = 0; n < 2; ++n) _Pragma("unroll") for (int k = 0; k < 2; ++k) \
;         acc[ai][bj][m][n] = __builtin_amdgcn_mfma_f32_16x16x32_bf16(Bt[n][k], At[m][k], acc[ai][bj][m][n], 0, 0, 0); __builtin_amdgcn_s_setprio(0); } while (0)
; #define PG8_WAIT_V(n) asm volatile("s_waitcnt vmcnt(" #n ")" ::: "memory")
; #define PG8_WAIT_L(n) asm volatile("s_waitcnt lgkmcnt(" #n ")" ::: "memory")
; #define PG8_BAR __builtin_amdgcn_s_barrier()
; #define PG8_SCHED __builtin_amdgcn_sched_barrier(0)
; template <class Epi, class Sched>
; DI void gemm_phase(LAS unsigned char* lds, const int wv, const int lda, const int ldb, const Sched& S, const Epi& E) {
;     ...
;             PG8_WAIT_V(8); PG8_WAIT_L(0); PG8_BAR; PG8_MMA(1, 0, At, B0); PG8_MMA(1, 1, At, B1); PG8_BAR; PG8_SCHED;
;             PG8_LDB(B0, 1, 0); PG8_LDB(B1, 1, 1); PG8_SCHED; PG8_LDA(At, 1, 0); PG8_STAGE(PG8_SA(0, 1), a2 + hstepA, voffA);
;             PG8_WAIT_V(8); PG8_WAIT_L(0); PG8_BAR; PG8_MMA(0, 0, At, B0); PG8_MMA(0, 1, At, B1); PG8_BAR; PG8_SCHED;
	v_mfma_f32_16x16x32_bf16 v[92:95], v[104:107], v[178:181], 0
	v_mfma_f32_16x16x32_bf16 v[88:91], v[150:153], v[178:181], 0
	v_mfma_f32_16x16x32_bf16 v[84:87], v[104:107], v[204:207], 0
	v_mfma_f32_16x16x32_bf16 v[80:83], v[150:153], v[204:207], 0
	v_mfma_f32_16x16x32_bf16 v[76:79], v[104:107], v[212:215], 0
	v_mfma_f32_16x16x32_bf16 v[72:75], v[150:153], v[212:215], 0
	v_mfma_f32_16x16x32_bf16 v[68:71], v[104:107], v[220:223], 0
	v_mfma_f32_16x16x32_bf16 v[64:67], v[150:153], v[220:223], 0
	v_mfma_f32_16x16x32_bf16 v[92:95], v[108:111], v[200:203], v[92:95]
	v_mfma_f32_16x16x32_bf16 v[88:91], v[154:157], v[200:203], v[88:91]
	v_mfma_f32_16x16x32_bf16 v[84:87], v[108:111], v[208:211], v[84:87]
	v_mfma_f32_16x16x32_bf16 v[80:83], v[154:157], v[208:211], v[80:83]
	v_mfma_f32_16x16x32_bf16 v[76:79], v[108:111], v[216:219], v[76:79]
	v_mfma_f32_16x16x32_bf16 v[72:75], v[154:157], v[216:219], v[72:75]
	v_mfma_f32_16x16x32_bf16 v[68:71], v[108:111], v[234:237], v[68:71]
	v_mfma_f32_16x16x32_bf16 v[64:67], v[154:157], v[234:237], v[64:67]
	v_mfma_f32_16x16x32_bf16 v[28:31], v[158:161], v[178:181], 0
	v_mfma_f32_16x16x32_bf16 v[24:27], v[166:169], v[178:181], 0
	v_mfma_f32_16x16x32_bf16 v[20:23], v[158:161], v[204:207], 0
	v_mfma_f32_16x16x32_bf16 v[16:19], v[166:169], v[204:207], 0
	v_mfma_f32_16x16x32_bf16 v[12:15], v[158:161], v[212:215], 0
	v_mfma_f32_16x16x32_bf16 v[8:11], v[166:169], v[212:215], 0
	v_mfma_f32_16x16x32_bf16 v[4:7], v[158:161], v[220:223], 0
	v_mfma_f32_16x16x32_bf16 v[0:3], v[166:169], v[220:223], 0
	v_mfma_f32_16x16x32_bf16 v[28:31], v[162:165], v[200:203], v[28:31]
	v_mfma_f32_16x16x32_bf16 v[24:27], v[174:177], v[200:203], v[24:27]
	v_mfma_f32_16x16x32_bf16 v[20:23], v[162:165], v[208:211], v[20:23]
	v_mfma_f32_16x16x32_bf16 v[16:19], v[174:177], v[208:211], v[16:19]
	v_mfma_f32_16x16x32_bf16 v[12:15], v[162:165], v[216:219], v[12:15]
	v_mfma_f32_16x16x32_bf16 v[8:11], v[174:177], v[216:219], v[8:11]
	v_mfma_f32_16x16x32_bf16 v[4:7], v[162:165], v[234:237], v[4:7]
	v_mfma_f32_16x16x32_bf16 v[0:3], v[174:177], v[234:237], v[0:3]
	s_barrier
	s_add_i32 s33, 0, 0x18000
	s_add_i32 s61, 0, 0x1c000
	v_add_u32_e32 v154, s33, v170
	v_add_u32_e32 v173, s61, v170
	ds_read_b128 v[104:107], v154
	ds_read_b128 v[108:111], v154 offset:1024
	ds_read_b128 v[150:153], v154 offset:2048
	ds_read_b128 v[154:157], v154 offset:3072
	ds_read_b128 v[158:161], v173
	ds_read_b128 v[162:165], v173 offset:1024
	ds_read_b128 v[166:169], v173 offset:2048
	ds_read_b128 v[174:177], v173 offset:3072
	s_add_u32 s38, s38, 0x80000
	s_addc_u32 s39, s39, 0
	s_mov_b32 m0, s49
	v_lshl_add_u64 v[198:199], s[38:39], 0, v[136:137]
	ds_read_b128 v[178:181], v172 offset:32768
	ds_read_b128 v[200:203], v172 offset:33792
	ds_read_b128 v[204:207], v172 offset:34816
	ds_read_b128 v[208:211], v172 offset:35840
	ds_read_b128 v[212:215], v172 offset:36864
	ds_read_b128 v[216:219], v172 offset:37888
	ds_read_b128 v[220:223], v172 offset:38912
	ds_read_b128 v[234:237], v172 offset:39936
	global_load_lds_dwordx4 v[198:199], off
	v_lshl_add_u64 v[198:199], s[38:39], 0, v[140:141]
	s_mov_b32 m0, s50
	s_nop 0
	global_load_lds_dwordx4 v[198:199], off
	s_waitcnt vmcnt(8) lgkmcnt(0)
	s_barrier
	v_mfma_f32_16x16x32_bf16 v[132:135], v[104:107], v[178:181], v[132:135]
	v_mfma_f32_16x16x32_bf16 v[128:131], v[150:153], v[178:181], v[128:131]
	v_mfma_f32_16x16x32_bf16 v[124:127], v[104:107], v[204:207], v[124:127]
	v_mfma_f32_16x16x32_bf16 v[120:123], v[150:153], v[204:207], v[120:123]
	v_mfma_f32_16x16x32_bf16 v[116:119], v[104:107], v[212:215], v[116:119]
	v_mfma_f32_16x16x32_bf16 v[112:115], v[150:153], v[212:215], v[112:115]
	v_mfma_f32_16x16x32_bf16 v[100:103], v[104:107], v[220:223], v[100:103]
	v_mfma_f32_16x16x32_bf16 v[96:99], v[150:153], v[220:223], v[96:99]
	v_mfma_f32_16x16x32_bf16 v[132:135], v[108:111], v[200:203], v[132:135]
	v_mfma_f32_16x16x32_bf16 v[128:131], v[154:157], v[200:203], v[128:131]
	v_mfma_f32_16x16x32_bf16 v[124:127], v[108:111], v[208:211], v[124:127]
	v_mfma_f32_16x16x32_bf16 v[120:123], v[154:157], v[208:211], v[120:123]
	v_mfma_f32_16x16x32_bf16 v[116:119], v[108:111], v[216:219], v[116:119]
	v_mfma_f32_16x16x32_bf16 v[112:115], v[154:157], v[216:219], v[112:115]
	v_mfma_f32_16x16x32_bf16 v[100:103], v[108:111], v[234:237], v[100:103]
	v_mfma_f32_16x16x32_bf16 v[96:99], v[154:157], v[234:237], v[96:99]
	v_mfma_f32_16x16x32_bf16 v[60:63], v[158:161], v[178:181], v[60:63]
	v_mfma_f32_16x16x32_bf16 v[56:59], v[166:169], v[178:181], v[56:59]
	v_mfma_f32_16x16x32_bf16 v[52:55], v[158:161], v[204:207], v[52:55]
	v_mfma_f32_16x16x32_bf16 v[48:51], v[166:169], v[204:207], v[48:51]
	v_mfma_f32_16x16x32_bf16 v[44:47], v[158:161], v[212:215], v[44:47]
	v_mfma_f32_16x16x32_bf16 v[40:43], v[166:169], v[212:215], v[40:43]
	v_mfma_f32_16x16x32_bf16 v[36:39], v[158:161], v[220:223], v[36:39]
	v_mfma_f32_16x16x32_bf16 v[32:35], v[166:169], v[220:223], v[32:35]
	v_mfma_f32_16x16x32_bf16 v[60:63], v[162:165], v[200:203], v[60:63]
	v_mfma_f32_16x16x32_bf16 v[56:59], v[174:177], v[200:203], v[56:59]
	v_mfma_f32_16x16x32_bf16 v[52:55], v[162:165], v[208:211], v[52:55]
	v_mfma_f32_16x16x32_bf16 v[48:51], v[174:177], v[208:211], v[48:51]
	v_mfma_f32_16x16x32_bf16 v[44:47], v[162:165], v[216:219], v[44:47]
	v_mfma_f32_16x16x32_bf16 v[40:43], v[174:177], v[216:219], v[40:43]
	v_mfma_f32_16x16x32_bf16 v[36:39], v[162:165], v[234:237], v[36:39]
	v_mfma_f32_16x16x32_bf16 v[32:35], v[174:177], v[234:237], v[32:35]
	s_barrier
; #define PG8_STAGE(bufoff, gbase, voff) do { _Pragma("unroll") for (int _i = 0; _i < 2; ++_i) \
;         __builtin_amdgcn_global_load_lds((const unsigned*)((const char*)(gbase) + (voff)[_i]), (LAS unsigned*)(lds + (bufoff) + ldsw + _i * 8192), 16, 0, 0); } while (0)
; #define PG8_LDA(dst, b, h) do { _Pragma("unroll") for (int m = 0; m < 4; ++m) _Pragma("unroll") for (int k = 0; k < 2; ++k) dst[m][k] = *(const LAS bf16x8*)(lds + PG8_SA(b, h) + aoff + m * 2048 + k * 1024); } while (0)
; #define PG8_MMA(ai, bj, At, Bt) do { __builtin_amdgcn_s_setprio(1); _Pragma("unroll") for (int m = 0; m < 4; ++m) _Pragma("unroll") for (int n = 0; n < 2; ++n) _Pragma("unroll") for (int k = 0; k < 2; ++k) \
;         acc[ai][bj][m][n] = __builtin_amdgcn_mfma_f32_16x16x32_bf16(Bt[n][k], At[m][k], acc[ai][bj][m][n], 0, 0, 0); __builtin_amdgcn_s_setprio(0); } while (0)
; #define PG8_WAIT_V(n) asm volatile("s_waitcnt vmcnt(" #n ")" ::: "memory")
; #define PG8_WAIT_L(n) asm volatile("s_waitcnt lgkmcnt(" #n ")" ::: "memory")
; #define PG8_BAR __builtin_amdgcn_s_barrier()
; #define PG8_SCHED __builtin_amdgcn_sched_barrier(0)
; template <class Epi, class Sched>
; DI void gemm_phase(LAS unsigned char* lds, const int wv, const int lda, const int ldb, const Sched& S, const Epi& E) {
;     ...
;             PG8_LDA(At, 1, 1); PG8_STAGE(PG8_SB(1, 0), b3, voffB); PG8_STAGE(PG8_SB(1, 1), b3 + hstepB, voffB); PG8_STAGE(PG8_SA(1, 0), a3, voffA);
;             PG8_WAIT_V(8); PG8_WAIT_L(0); PG8_BAR; PG8_MMA(1, 0, At, B0); PG8_MMA(1, 1, At, B1); PG8_BAR; PG8_SCHED;
;         }
	s_add_i32 s33, s33, s47
	v_lshl_add_u64 v[182:183], v[182:183], 0, s[28:29]
	s_mov_b32 m0, s33
	ds_read_b128 v[178:181], v172 offset:49152
	ds_read_b128 v[200:203], v172 offset:50176
	ds_read_b128 v[204:207], v172 offset:51200
	ds_read_b128 v[208:211], v172 offset:52224
	ds_read_b128 v[212:215], v172 offset:53248
	ds_read_b128 v[216:219], v172 offset:54272
	ds_read_b128 v[220:223], v172 offset:55296
	ds_read_b128 v[234:237], v172 offset:56320
	global_load_lds_dwordx4 v[182:183], off
	s_add_i32 m0, s33, 0x2000
	s_add_u32 s36, s36, 0x80080
	v_lshl_add_u64 v[182:183], v[188:189], 0, s[28:29]
	s_addc_u32 s37, s37, 0
	s_add_i32 s33, s61, s47
	global_load_lds_dwordx4 v[182:183], off
	v_lshl_add_u64 v[182:183], s[36:37], 0, v[138:139]
	s_mov_b32 m0, s33
	s_nop 0
	global_load_lds_dwordx4 v[182:183], off
	v_lshl_add_u64 v[182:183], s[36:37], 0, v[142:143]
	s_add_i32 m0, s33, 0x2000
	s_nop 0
	global_load_lds_dwordx4 v[182:183], off
	v_lshl_add_u64 v[182:183], v[190:191], 0, s[28:29]
	s_mov_b32 m0, s52
	s_nop 0
	global_load_lds_dwordx4 v[182:183], off
	v_lshl_add_u64 v[182:183], v[196:197], 0, s[28:29]
	s_mov_b32 m0, s53
	s_nop 0
	global_load_lds_dwordx4 v[182:183], off
	s_waitcnt vmcnt(8) lgkmcnt(0)
	s_barrier
	v_mfma_f32_16x16x32_bf16 v[92:95], v[104:107], v[178:181], v[92:95]
	v_mfma_f32_16x16x32_bf16 v[88:91], v[150:153], v[178:181], v[88:91]
	v_mfma_f32_16x16x32_bf16 v[84:87], v[104:107], v[204:207], v[84:87]
	v_mfma_f32_16x16x32_bf16 v[80:83], v[150:153], v[204:207], v[80:83]
	v_mfma_f32_16x16x32_bf16 v[76:79], v[104:107], v[212:215], v[76:79]
	v_mfma_f32_16x16x32_bf16 v[72:75], v[150:153], v[212:215], v[72:75]
	v_mfma_f32_16x16x32_bf16 v[68:71], v[104:107], v[220:223], v[68:71]
	v_mfma_f32_16x16x32_bf16 v[64:67], v[150:153], v[220:223], v[64:67]
	v_mfma_f32_16x16x32_bf16 v[92:95], v[108:111], v[200:203], v[92:95]
	v_mfma_f32_16x16x32_bf16 v[88:91], v[154:157], v[200:203], v[88:91]
	v_mfma_f32_16x16x32_bf16 v[84:87], v[108:111], v[208:211], v[84:87]
	v_mfma_f32_16x16x32_bf16 v[80:83], v[154:157], v[208:211], v[80:83]
	v_mfma_f32_16x16x32_bf16 v[76:79], v[108:111], v[216:219], v[76:79]
	v_mfma_f32_16x16x32_bf16 v[72:75], v[154:157], v[216:219], v[72:75]
	v_mfma_f32_16x16x32_bf16 v[68:71], v[108:111], v[234:237], v[68:71]
	v_mfma_f32_16x16x32_bf16 v[64:67], v[154:157], v[234:237], v[64:67]
	v_mfma_f32_16x16x32_bf16 v[28:31], v[158:161], v[178:181], v[28:31]
	v_mfma_f32_16x16x32_bf16 v[24:27], v[166:169], v[178:181], v[24:27]
	v_mfma_f32_16x16x32_bf16 v[20:23], v[158:161], v[204:207], v[20:23]
	v_mfma_f32_16x16x32_bf16 v[16:19], v[166:169], v[204:207], v[16:19]
	v_mfma_f32_16x16x32_bf16 v[12:15], v[158:161], v[212:215], v[12:15]
	v_mfma_f32_16x16x32_bf16 v[8:11], v[166:169], v[212:215], v[8:11]
	v_mfma_f32_16x16x32_bf16 v[4:7], v[158:161], v[220:223], v[4:7]
	v_mfma_f32_16x16x32_bf16 v[0:3], v[166:169], v[220:223], v[0:3]
	v_mfma_f32_16x16x32_bf16 v[28:31], v[162:165], v[200:203], v[28:31]
	v_mfma_f32_16x16x32_bf16 v[24:27], v[174:177], v[200:203], v[24:27]
	v_mfma_f32_16x16x32_bf16 v[20:23], v[162:165], v[208:211], v[20:23]
	v_mfma_f32_16x16x32_bf16 v[16:19], v[174:177], v[208:211], v[16:19]
	v_mfma_f32_16x16x32_bf16 v[12:15], v[162:165], v[216:219], v[12:15]
	v_mfma_f32_16x16x32_bf16 v[8:11], v[174:177], v[216:219], v[8:11]
	v_mfma_f32_16x16x32_bf16 v[4:7], v[162:165], v[234:237], v[4:7]
	v_mfma_f32_16x16x32_bf16 v[0:3], v[174:177], v[234:237], v[0:3]
	s_barrier
	s_add_i32 s23, s23, 2
	s_add_u32 s34, s34, 0x100
	s_addc_u32 s35, s35, 0
	s_add_u32 s17, s17, 0x100
	s_addc_u32 s19, s19, 0

;     DI bool next(int i, Unit& u) const { const long L = (long)i * G + c; if (L >= T.nwg) return false; T.map((int)L, u.pm, u.pn); u.seg = 0; return true; }
;     DI bool next(int i, Unit& u) const { const int ti = i / 3; const long L = (long)ti * G + c; if (L >= T.nwg) return false; T.map((int)L, u.pm, u.pn); u.seg = i - 3 * ti; return true; }
;     DI const char* aptr(const Unit& u) const { return A + (size_t)u.pm * ta + (size_t)kofs(u.seg) * 2; }
;     DI const char* bptr(const Unit& u) const { return B + (size_t)u.pn * tb + (size_t)kofs(u.seg) * 2; }
; #define PG8_STAGE(bufoff, gbase, voff) do { _Pragma("unroll") for (int _i = 0; _i < 2; ++_i) \
;         __builtin_amdgcn_global_load_lds((const unsigned*)((const char*)(gbase) + (voff)[_i]), (LAS unsigned*)(lds + (bufoff) + ldsw + _i * 8192), 16, 0, 0); } while (0)
; #define PG8_LDA(dst, b, h) do { _Pragma("unroll") for (int m = 0; m < 4; ++m) _Pragma("unroll") for (int k = 0; k < 2; ++k) dst[m][k] = *(const LAS bf16x8*)(lds + PG8_SA(b, h) + aoff + m * 2048 + k * 1024); } while (0)
; #define PG8_WAIT_V(n) asm volatile("s_waitcnt vmcnt(" #n ")" ::: "memory")
; #define PG8_WAIT_L(n) asm volatile("s_waitcnt lgkmcnt(" #n ")" ::: "memory")
; template <class Epi, class Sched>
; DI void gemm_phase(LAS unsigned char* lds, const int wv, const int lda, const int ldb, const Sched& S, const Epi& E) {
;     ...
;         const bool has_next = S.next(ui + 1, nxt);
;         const char* nA = has_next ? S.aptr(nxt) : cA; const char* nB = has_next ? S.bptr(nxt) : cB;
;         for (int t = 0; t < nt; t += 2) {
;             const bool last = (t == nt - 2);
;             const char* a1 = cA + (size_t)(t + 1) * kstep;
;             const char* a2 = last ? nA : cA + (size_t)(t + 2) * kstep; const char* b2 = last ? nB : cB + (size_t)(t + 2) * kstep;
;             const char* a3 = a2 + kstep; const char* b3 = b2 + kstep;
;             PG8_LDB(B0, 0, 0); PG8_LDB(B1, 0, 1); PG8_SCHED; PG8_LDA(At, 0, 0); PG8_STAGE(PG8_SA(1, 1), a1 + hstepA, voffA);
;             PG8_WAIT_V(8); PG8_WAIT_L(0); PG8_BAR; PG8_MMA(0, 0, At, B0); PG8_MMA(0, 1, At, B1); PG8_BAR; PG8_SCHED;
;             PG8_LDA(At, 0, 1); PG8_STAGE(PG8_SB(0, 0), b2, voffB); PG8_STAGE(PG8_SB(0, 1), b2 + hstepB, voffB); PG8_STAGE(PG8_SA(0, 0), a2, voffA);
;             PG8_WAIT_V(8); PG8_WAIT_L(0); PG8_BAR; PG8_MMA(1, 0, At, B0); PG8_MMA(1, 1, At, B1); PG8_BAR; PG8_SCHED;
.LBB0_1098:
	s_add_u32 s0, s24, 0x100
	s_addc_u32 s1, s25, 0
	s_mov_b32 s49, -2
	s_add_u32 s24, s22, 0x100
	s_addc_u32 s25, s23, 0
	s_add_i32 s50, 0, 0x10000
	s_cmp_eq_u32 s49, 8
	s_cselect_b32 s31, s7, s25
	s_cselect_b32 s30, s6, s24
	s_cselect_b32 s27, s19, s1
	s_cselect_b32 s26, s18, s0
	s_add_i32 s51, 0, 0x14000
	v_add_u32_e32 v108, s50, v204
	v_add_u32_e32 v156, s51, v204
	ds_read_b128 v[64:67], v108
	ds_read_b128 v[68:71], v108 offset:1024
	ds_read_b128 v[104:107], v108 offset:2048
	ds_read_b128 v[108:111], v108 offset:3072
	ds_read_b128 v[144:147], v156
	ds_read_b128 v[148:151], v156 offset:1024
	ds_read_b128 v[152:155], v156 offset:2048
	ds_read_b128 v[156:159], v156 offset:3072
	v_lshl_add_u64 v[182:183], s[22:23], 0, v[174:175]
	s_add_i32 m0, s38, 0xc000
	ds_read_b128 v[160:163], v206
	ds_read_b128 v[164:167], v206 offset:1024
	ds_read_b128 v[178:181], v206 offset:2048
	ds_read_b128 v[188:191], v206 offset:3072
	ds_read_b128 v[196:199], v206 offset:4096
	ds_read_b128 v[200:203], v206 offset:5120
	ds_read_b128 v[208:211], v206 offset:6144
	ds_read_b128 v[212:215], v206 offset:7168
	global_load_lds_dwordx4 v[182:183], off
	v_lshl_add_u64 v[182:183], s[22:23], 0, v[176:177]
	s_add_i32 m0, s38, 0xe000
	s_nop 0
	global_load_lds_dwordx4 v[182:183], off
	s_waitcnt vmcnt(8) lgkmcnt(0)
	s_barrier
	v_mfma_f32_16x16x32_bf16 v[140:143], v[64:67], v[160:163], 0
	v_mfma_f32_16x16x32_bf16 v[136:139], v[104:107], v[160:163], 0
	v_mfma_f32_16x16x32_bf16 v[132:135], v[64:67], v[178:181], 0
	v_mfma_f32_16x16x32_bf16 v[128:131], v[104:107], v[178:181], 0
	v_mfma_f32_16x16x32_bf16 v[124:127], v[64:67], v[196:199], 0
	v_mfma_f32_16x16x32_bf16 v[120:123], v[104:107], v[196:199], 0
	v_mfma_f32_16x16x32_bf16 v[116:119], v[64:67], v[208:211], 0
	v_mfma_f32_16x16x32_bf16 v[112:115], v[104:107], v[208:211], 0
	v_mfma_f32_16x16x32_bf16 v[140:143], v[68:71], v[164:167], v[140:143]
	v_mfma_f32_16x16x32_bf16 v[136:139], v[108:111], v[164:167], v[136:139]
	v_mfma_f32_16x16x32_bf16 v[132:135], v[68:71], v[188:191], v[132:135]
	v_mfma_f32_16x16x32_bf16 v[128:131], v[108:111], v[188:191], v[128:131]
	v_mfma_f32_16x16x32_bf16 v[124:127], v[68:71], v[200:203], v[124:127]
	v_mfma_f32_16x16x32_bf16 v[120:123], v[108:111], v[200:203], v[120:123]
	v_mfma_f32_16x16x32_bf16 v[116:119], v[68:71], v[212:215], v[116:119]
	v_mfma_f32_16x16x32_bf16 v[112:115], v[108:111], v[212:215], v[112:115]
	v_mfma_f32_16x16x32_bf16 v[100:103], v[144:147], v[160:163], 0
	v_mfma_f32_16x16x32_bf16 v[96:99], v[152:155], v[160:163], 0
	v_mfma_f32_16x16x32_bf16 v[92:95], v[144:147], v[178:181], 0
	v_mfma_f32_16x16x32_bf16 v[88:91], v[152:155], v[178:181], 0
	v_mfma_f32_16x16x32_bf16 v[84:87], v[144:147], v[196:199], 0
	v_mfma_f32_16x16x32_bf16 v[80:83], v[152:155], v[196:199], 0
	v_mfma_f32_16x16x32_bf16 v[76:79], v[144:147], v[208:211], 0
	v_mfma_f32_16x16x32_bf16 v[72:75], v[152:155], v[208:211], 0
	v_mfma_f32_16x16x32_bf16 v[100:103], v[148:151], v[164:167], v[100:103]
	v_mfma_f32_16x16x32_bf16 v[96:99], v[156:159], v[164:167], v[96:99]
	v_mfma_f32_16x16x32_bf16 v[92:95], v[148:151], v[188:191], v[92:95]
	v_mfma_f32_16x16x32_bf16 v[88:91], v[156:159], v[188:191], v[88:91]
	v_mfma_f32_16x16x32_bf16 v[84:87], v[148:151], v[200:203], v[84:87]
	v_mfma_f32_16x16x32_bf16 v[80:83], v[156:159], v[200:203], v[80:83]
	v_mfma_f32_16x16x32_bf16 v[76:79], v[148:151], v[212:215], v[76:79]
	v_mfma_f32_16x16x32_bf16 v[72:75], v[156:159], v[212:215], v[72:75]
	s_barrier
	s_add_i32 s22, s50, s36
	v_lshl_add_u64 v[182:183], s[26:27], 0, v[184:185]
	s_mov_b32 m0, s22
	ds_read_b128 v[160:163], v206 offset:16384
	ds_read_b128 v[164:167], v206 offset:17408
	ds_read_b128 v[178:181], v206 offset:18432
	ds_read_b128 v[188:191], v206 offset:19456
	ds_read_b128 v[196:199], v206 offset:20480
	ds_read_b128 v[200:203], v206 offset:21504
	ds_read_b128 v[208:211], v206 offset:22528
	ds_read_b128 v[212:215], v206 offset:23552
	global_load_lds_dwordx4 v[182:183], off
	s_add_i32 m0, s22, 0x2000
	s_add_u32 s22, s26, 0x30000
	v_lshl_add_u64 v[216:217], s[26:27], 0, v[168:169]
	s_addc_u32 s23, s27, 0
	s_add_i32 s50, s51, s36
	global_load_lds_dwordx4 v[216:217], off
	v_lshl_add_u64 v[218:219], s[22:23], 0, v[184:185]
	s_mov_b32 m0, s50
	v_lshl_add_u64 v[220:221], s[30:31], 0, v[170:171]
	global_load_lds_dwordx4 v[218:219], off
	v_lshl_add_u64 v[218:219], s[22:23], 0, v[168:169]
	s_add_i32 m0, s50, 0x2000
	s_nop 0
	global_load_lds_dwordx4 v[218:219], off
	v_lshl_add_u64 v[218:219], s[30:31], 0, v[172:173]
	s_mov_b32 m0, s38
	s_nop 0
	global_load_lds_dwordx4 v[218:219], off
	s_mov_b32 m0, s39
	s_nop 0
	global_load_lds_dwordx4 v[220:221], off
	s_waitcnt vmcnt(8) lgkmcnt(0)
	s_barrier
; #define PG8_STAGE(bufoff, gbase, voff) do { _Pragma("unroll") for (int _i = 0; _i < 2; ++_i) \
;         __builtin_amdgcn_global_load_lds((const unsigned*)((const char*)(gbase) + (voff)[_i]), (LAS unsigned*)(lds + (bufoff) + ldsw + _i * 8192), 16, 0, 0); } while (0)
; #define PG8_LDA(dst, b, h) do { _Pragma("unroll") for (int m = 0; m < 4; ++m) _Pragma("unroll") for (int k = 0; k < 2; ++k) dst[m][k] = *(const LAS bf16x8*)(lds + PG8_SA(b, h) + aoff + m * 2048 + k * 1024); } while (0)
; #define PG8_LDB(dst, b, h) do { _Pragma("unroll") for (int n = 0; n < 2; ++n) _Pragma("unroll") for (int k = 0; k < 2; ++k) dst[n][k] = *(const LAS bf16x8*)(lds + PG8_SB(b, h) + boff + n * 2048 + k * 1024); } while (0)
; #define PG8_MMA(ai, bj, At, Bt) do { __builtin_amdgcn_s_setprio(1); _Pragma("unroll") for (int m = 0; m < 4; ++m) _Pragma("unroll") for (int n = 0; n < 2; ++n) _Pragma("unroll") for (int k = 0; k < 2; ++k) \
;         acc[ai][bj][m][n] = __builtin_amdgcn_mfma_f32_16x16x32_bf16(Bt[n][k], At[m][k], acc[ai][bj][m][n], 0, 0, 0); __builtin_amdgcn_s_setprio(0); } while (0)
; #define PG8_WAIT_V(n) asm volatile("s_waitcnt vmcnt(" #n ")" ::: "memory")
; #define PG8_WAIT_L(n) asm volatile("s_waitcnt lgkmcnt(" #n ")" ::: "memory")
; #define PG8_BAR __builtin_amdgcn_s_barrier()
; #define PG8_SCHED __builtin_amdgcn_sched_barrier(0)
; template <class Epi, class Sched>
; DI void gemm_phase(LAS unsigned char* lds, const int wv, const int lda, const int ldb, const Sched& S, const Epi& E) {
;     ...
;             PG8_WAIT_V(8); PG8_WAIT_L(0); PG8_BAR; PG8_MMA(1, 0, At, B0); PG8_MMA(1, 1, At, B1); PG8_BAR; PG8_SCHED;
;             PG8_LDB(B0, 1, 0); PG8_LDB(B1, 1, 1); PG8_SCHED; PG8_LDA(At, 1, 0); PG8_STAGE(PG8_SA(0, 1), a2 + hstepA, voffA);
;             PG8_WAIT_V(8); PG8_WAIT_L(0); PG8_BAR; PG8_MMA(0, 0, At, B0); PG8_MMA(0, 1, At, B1); PG8_BAR; PG8_SCHED;
	v_mfma_f32_16x16x32_bf16 v[60:63], v[64:67], v[160:163], 0
	v_mfma_f32_16x16x32_bf16 v[56:59], v[104:107], v[160:163], 0
	v_mfma_f32_16x16x32_bf16 v[52:55], v[64:67], v[178:181], 0
	v_mfma_f32_16x16x32_bf16 v[48:51], v[104:107], v[178:181], 0
	v_mfma_f32_16x16x32_bf16 v[44:47], v[64:67], v[196:199], 0
	v_mfma_f32_16x16x32_bf16 v[40:43], v[104:107], v[196:199], 0
	v_mfma_f32_16x16x32_bf16 v[36:39], v[64:67], v[208:211], 0
	v_mfma_f32_16x16x32_bf16 v[32:35], v[104:107], v[208:211], 0
	v_mfma_f32_16x16x32_bf16 v[60:63], v[68:71], v[164:167], v[60:63]
	v_mfma_f32_16x16x32_bf16 v[56:59], v[108:111], v[164:167], v[56:59]
	v_mfma_f32_16x16x32_bf16 v[52:55], v[68:71], v[188:191], v[52:55]
	v_mfma_f32_16x16x32_bf16 v[48:51], v[108:111], v[188:191], v[48:51]
	v_mfma_f32_16x16x32_bf16 v[44:47], v[68:71], v[200:203], v[44:47]
	v_mfma_f32_16x16x32_bf16 v[40:43], v[108:111], v[200:203], v[40:43]
	v_mfma_f32_16x16x32_bf16 v[36:39], v[68:71], v[212:215], v[36:39]
	v_mfma_f32_16x16x32_bf16 v[32:35], v[108:111], v[212:215], v[32:35]
	v_mfma_f32_16x16x32_bf16 v[28:31], v[144:147], v[160:163], 0
	v_mfma_f32_16x16x32_bf16 v[24:27], v[152:155], v[160:163], 0
	v_mfma_f32_16x16x32_bf16 v[20:23], v[144:147], v[178:181], 0
	v_mfma_f32_16x16x32_bf16 v[16:19], v[152:155], v[178:181], 0
	v_mfma_f32_16x16x32_bf16 v[12:15], v[144:147], v[196:199], 0
	v_mfma_f32_16x16x32_bf16 v[8:11], v[152:155], v[196:199], 0
	v_mfma_f32_16x16x32_bf16 v[4:7], v[144:147], v[208:211], 0
	v_mfma_f32_16x16x32_bf16 v[0:3], v[152:155], v[208:211], 0
	v_mfma_f32_16x16x32_bf16 v[28:31], v[148:151], v[164:167], v[28:31]
	v_mfma_f32_16x16x32_bf16 v[24:27], v[156:159], v[164:167], v[24:27]
	v_mfma_f32_16x16x32_bf16 v[20:23], v[148:151], v[188:191], v[20:23]
	v_mfma_f32_16x16x32_bf16 v[16:19], v[156:159], v[188:191], v[16:19]
	v_mfma_f32_16x16x32_bf16 v[12:15], v[148:151], v[200:203], v[12:15]
	v_mfma_f32_16x16x32_bf16 v[8:11], v[156:159], v[200:203], v[8:11]
	v_mfma_f32_16x16x32_bf16 v[4:7], v[148:151], v[212:215], v[4:7]
	v_mfma_f32_16x16x32_bf16 v[0:3], v[156:159], v[212:215], v[0:3]
	s_barrier
	s_add_i32 s50, 0, 0x18000
	s_add_i32 s51, 0, 0x1c000
	v_add_u32_e32 v108, s50, v204
	v_add_u32_e32 v156, s51, v204
	ds_read_b128 v[64:67], v108
	ds_read_b128 v[68:71], v108 offset:1024
	ds_read_b128 v[104:107], v108 offset:2048
	ds_read_b128 v[108:111], v108 offset:3072
	ds_read_b128 v[144:147], v156
	ds_read_b128 v[148:151], v156 offset:1024
	ds_read_b128 v[152:155], v156 offset:2048
	ds_read_b128 v[156:159], v156 offset:3072
	s_add_u32 s22, s30, 0x30000
	s_addc_u32 s23, s31, 0
	s_mov_b32 m0, s40
	v_lshl_add_u64 v[222:223], s[22:23], 0, v[172:173]
	ds_read_b128 v[160:163], v206 offset:32768
	ds_read_b128 v[164:167], v206 offset:33792
	ds_read_b128 v[178:181], v206 offset:34816
	ds_read_b128 v[188:191], v206 offset:35840
	ds_read_b128 v[196:199], v206 offset:36864
	ds_read_b128 v[200:203], v206 offset:37888
	ds_read_b128 v[208:211], v206 offset:38912
	ds_read_b128 v[212:215], v206 offset:39936
	global_load_lds_dwordx4 v[222:223], off
	v_lshl_add_u64 v[222:223], s[22:23], 0, v[170:171]
	s_mov_b32 m0, s41
	s_nop 0
	global_load_lds_dwordx4 v[222:223], off
	s_waitcnt vmcnt(8) lgkmcnt(0)
	s_barrier
	v_mfma_f32_16x16x32_bf16 v[140:143], v[64:67], v[160:163], v[140:143]
	v_mfma_f32_16x16x32_bf16 v[136:139], v[104:107], v[160:163], v[136:139]
	v_mfma_f32_16x16x32_bf16 v[132:135], v[64:67], v[178:181], v[132:135]
	v_mfma_f32_16x16x32_bf16 v[128:131], v[104:107], v[178:181], v[128:131]
	v_mfma_f32_16x16x32_bf16 v[124:127], v[64:67], v[196:199], v[124:127]
	v_mfma_f32_16x16x32_bf16 v[120:123], v[104:107], v[196:199], v[120:123]
	v_mfma_f32_16x16x32_bf16 v[116:119], v[64:67], v[208:211], v[116:119]
	v_mfma_f32_16x16x32_bf16 v[112:115], v[104:107], v[208:211], v[112:115]
	v_mfma_f32_16x16x32_bf16 v[140:143], v[68:71], v[164:167], v[140:143]
	v_mfma_f32_16x16x32_bf16 v[136:139], v[108:111], v[164:167], v[136:139]
	v_mfma_f32_16x16x32_bf16 v[132:135], v[68:71], v[188:191], v[132:135]
	v_mfma_f32_16x16x32_bf16 v[128:131], v[108:111], v[188:191], v[128:131]
	v_mfma_f32_16x16x32_bf16 v[124:127], v[68:71], v[200:203], v[124:127]
	v_mfma_f32_16x16x32_bf16 v[120:123], v[108:111], v[200:203], v[120:123]
	v_mfma_f32_16x16x32_bf16 v[116:119], v[68:71], v[212:215], v[116:119]
	v_mfma_f32_16x16x32_bf16 v[112:115], v[108:111], v[212:215], v[112:115]
	v_mfma_f32_16x16x32_bf16 v[100:103], v[144:147], v[160:163], v[100:103]
	v_mfma_f32_16x16x32_bf16 v[96:99], v[152:155], v[160:163], v[96:99]
	v_mfma_f32_16x16x32_bf16 v[92:95], v[144:147], v[178:181], v[92:95]
	v_mfma_f32_16x16x32_bf16 v[88:91], v[152:155], v[178:181], v[88:91]
	v_mfma_f32_16x16x32_bf16 v[84:87], v[144:147], v[196:199], v[84:87]
	v_mfma_f32_16x16x32_bf16 v[80:83], v[152:155], v[196:199], v[80:83]
	v_mfma_f32_16x16x32_bf16 v[76:79], v[144:147], v[208:211], v[76:79]
	v_mfma_f32_16x16x32_bf16 v[72:75], v[152:155], v[208:211], v[72:75]
	v_mfma_f32_16x16x32_bf16 v[100:103], v[148:151], v[164:167], v[100:103]
	v_mfma_f32_16x16x32_bf16 v[96:99], v[156:159], v[164:167], v[96:99]
	v_mfma_f32_16x16x32_bf16 v[92:95], v[148:151], v[188:191], v[92:95]
	v_mfma_f32_16x16x32_bf16 v[88:91], v[156:159], v[188:191], v[88:91]
	v_mfma_f32_16x16x32_bf16 v[84:87], v[148:151], v[200:203], v[84:87]
	v_mfma_f32_16x16x32_bf16 v[80:83], v[156:159], v[200:203], v[80:83]
	v_mfma_f32_16x16x32_bf16 v[76:79], v[148:151], v[212:215], v[76:79]
	v_mfma_f32_16x16x32_bf16 v[72:75], v[156:159], v[212:215], v[72:75]
	s_barrier
; #define PG8_STAGE(bufoff, gbase, voff) do { _Pragma("unroll") for (int _i = 0; _i < 2; ++_i) \
;         __builtin_amdgcn_global_load_lds((const unsigned*)((const char*)(gbase) + (voff)[_i]), (LAS unsigned*)(lds + (bufoff) + ldsw + _i * 8192), 16, 0, 0); } while (0)
; #define PG8_LDA(dst, b, h) do { _Pragma("unroll") for (int m = 0; m < 4; ++m) _Pragma("unroll") for (int k = 0; k < 2; ++k) dst[m][k] = *(const LAS bf16x8*)(lds + PG8_SA(b, h) + aoff + m * 2048 + k * 1024); } while (0)
; #define PG8_MMA(ai, bj, At, Bt) do { __builtin_amdgcn_s_setprio(1); _Pragma("unroll") for (int m = 0; m < 4; ++m) _Pragma("unroll") for (int n = 0; n < 2; ++n) _Pragma("unroll") for (int k = 0; k < 2; ++k) \
;         acc[ai][bj][m][n] = __builtin_amdgcn_mfma_f32_16x16x32_bf16(Bt[n][k], At[m][k], acc[ai][bj][m][n], 0, 0, 0); __builtin_amdgcn_s_setprio(0); } while (0)
; #define PG8_WAIT_V(n) asm volatile("s_waitcnt vmcnt(" #n ")" ::: "memory")
; #define PG8_WAIT_L(n) asm volatile("s_waitcnt lgkmcnt(" #n ")" ::: "memory")
; #define PG8_BAR __builtin_amdgcn_s_barrier()
; #define PG8_SCHED __builtin_amdgcn_sched_barrier(0)
; template <class Epi, class Sched>
; DI void gemm_phase(LAS unsigned char* lds, const int wv, const int lda, const int ldb, const Sched& S, const Epi& E) {
;     ...
;             PG8_LDA(At, 1, 1); PG8_STAGE(PG8_SB(1, 0), b3, voffB); PG8_STAGE(PG8_SB(1, 1), b3 + hstepB, voffB); PG8_STAGE(PG8_SA(1, 0), a3, voffA);
;             PG8_WAIT_V(8); PG8_WAIT_L(0); PG8_BAR; PG8_MMA(1, 0, At, B0); PG8_MMA(1, 1, At, B1); PG8_BAR; PG8_SCHED;
;         }
	s_add_i32 s22, s50, s36
	v_lshl_add_u64 v[182:183], v[182:183], 0, s[28:29]
	s_mov_b32 m0, s22
	ds_read_b128 v[160:163], v206 offset:49152
	ds_read_b128 v[164:167], v206 offset:50176
	ds_read_b128 v[178:181], v206 offset:51200
	ds_read_b128 v[188:191], v206 offset:52224
	ds_read_b128 v[196:199], v206 offset:53248
	ds_read_b128 v[200:203], v206 offset:54272
	ds_read_b128 v[208:211], v206 offset:55296
	ds_read_b128 v[212:215], v206 offset:56320
	global_load_lds_dwordx4 v[182:183], off
	s_add_i32 m0, s22, 0x2000
	s_add_u32 s22, s26, 0x30080
	v_lshl_add_u64 v[182:183], v[216:217], 0, s[28:29]
	s_addc_u32 s23, s27, 0
	s_add_i32 s26, s51, s36
	global_load_lds_dwordx4 v[182:183], off
	v_lshl_add_u64 v[182:183], s[22:23], 0, v[184:185]
	s_mov_b32 m0, s26
	s_nop 0
	global_load_lds_dwordx4 v[182:183], off
	v_lshl_add_u64 v[182:183], s[22:23], 0, v[168:169]
	s_add_i32 m0, s26, 0x2000
	s_nop 0
	global_load_lds_dwordx4 v[182:183], off
	v_lshl_add_u64 v[182:183], v[218:219], 0, s[28:29]
	s_mov_b32 m0, s20
	s_nop 0
	global_load_lds_dwordx4 v[182:183], off
	v_lshl_add_u64 v[182:183], v[220:221], 0, s[28:29]
	s_mov_b32 m0, s42
	s_nop 0
	global_load_lds_dwordx4 v[182:183], off
	s_waitcnt vmcnt(8) lgkmcnt(0)
	s_barrier
	v_mfma_f32_16x16x32_bf16 v[60:63], v[64:67], v[160:163], v[60:63]
	v_mfma_f32_16x16x32_bf16 v[56:59], v[104:107], v[160:163], v[56:59]
	v_mfma_f32_16x16x32_bf16 v[52:55], v[64:67], v[178:181], v[52:55]
	v_mfma_f32_16x16x32_bf16 v[48:51], v[104:107], v[178:181], v[48:51]
	v_mfma_f32_16x16x32_bf16 v[44:47], v[64:67], v[196:199], v[44:47]
	v_mfma_f32_16x16x32_bf16 v[40:43], v[104:107], v[196:199], v[40:43]
	v_mfma_f32_16x16x32_bf16 v[36:39], v[64:67], v[208:211], v[36:39]
	v_mfma_f32_16x16x32_bf16 v[32:35], v[104:107], v[208:211], v[32:35]
	v_mfma_f32_16x16x32_bf16 v[60:63], v[68:71], v[164:167], v[60:63]
	v_mfma_f32_16x16x32_bf16 v[56:59], v[108:111], v[164:167], v[56:59]
	v_mfma_f32_16x16x32_bf16 v[52:55], v[68:71], v[188:191], v[52:55]
	v_mfma_f32_16x16x32_bf16 v[48:51], v[108:111], v[188:191], v[48:51]
	v_mfma_f32_16x16x32_bf16 v[44:47], v[68:71], v[200:203], v[44:47]
	v_mfma_f32_16x16x32_bf16 v[40:43], v[108:111], v[200:203], v[40:43]
	v_mfma_f32_16x16x32_bf16 v[36:39], v[68:71], v[212:215], v[36:39]
	v_mfma_f32_16x16x32_bf16 v[32:35], v[108:111], v[212:215], v[32:35]
	v_mfma_f32_16x16x32_bf16 v[28:31], v[144:147], v[160:163], v[28:31]
	v_mfma_f32_16x16x32_bf16 v[24:27], v[152:155], v[160:163], v[24:27]
	v_mfma_f32_16x16x32_bf16 v[20:23], v[144:147], v[178:181], v[20:23]
	v_mfma_f32_16x16x32_bf16 v[16:19], v[152:155], v[178:181], v[16:19]
	v_mfma_f32_16x16x32_bf16 v[12:15], v[144:147], v[196:199], v[12:15]
	v_mfma_f32_16x16x32_bf16 v[8:11], v[152:155], v[196:199], v[8:11]
	v_mfma_f32_16x16x32_bf16 v[4:7], v[144:147], v[208:211], v[4:7]
	v_mfma_f32_16x16x32_bf16 v[0:3], v[152:155], v[208:211], v[0:3]
	v_mfma_f32_16x16x32_bf16 v[28:31], v[148:151], v[164:167], v[28:31]
	v_mfma_f32_16x16x32_bf16 v[24:27], v[156:159], v[164:167], v[24:27]
	v_mfma_f32_16x16x32_bf16 v[20:23], v[148:151], v[188:191], v[20:23]
	v_mfma_f32_16x16x32_bf16 v[16:19], v[156:159], v[188:191], v[16:19]
	v_mfma_f32_16x16x32_bf16 v[12:15], v[148:151], v[200:203], v[12:15]
	v_mfma_f32_16x16x32_bf16 v[8:11], v[156:159], v[200:203], v[8:11]
	v_mfma_f32_16x16x32_bf16 v[4:7], v[148:151], v[212:215], v[4:7]
	v_mfma_f32_16x16x32_bf16 v[0:3], v[156:159], v[212:215], v[0:3]
	s_barrier
	s_add_i32 s49, s49, 2
	s_add_u32 s0, s0, 0x100
	s_addc_u32 s1, s1, 0
	s_mov_b64 s[22:23], s[24:25]

;     DI bool next(int i, Unit& u) const { const long L = (long)i * G + c; if (L >= T.nwg) return false; T.map((int)L, u.pm, u.pn); u.seg = 0; return true; }
;     DI bool next(int i, Unit& u) const { const int ti = i / 3; const long L = (long)ti * G + c; if (L >= T.nwg) return false; T.map((int)L, u.pm, u.pn); u.seg = i - 3 * ti; return true; }
;     DI const char* aptr(const Unit& u) const { return A + (size_t)u.pm * ta + (size_t)kofs(u.seg) * 2; }
;     DI const char* bptr(const Unit& u) const { return B + (size_t)u.pn * tb + (size_t)kofs(u.seg) * 2; }
; #define PG8_STAGE(bufoff, gbase, voff) do { _Pragma("unroll") for (int _i = 0; _i < 2; ++_i) \
;         __builtin_amdgcn_global_load_lds((const unsigned*)((const char*)(gbase) + (voff)[_i]), (LAS unsigned*)(lds + (bufoff) + ldsw + _i * 8192), 16, 0, 0); } while (0)
; #define PG8_LDA(dst, b, h) do { _Pragma("unroll") for (int m = 0; m < 4; ++m) _Pragma("unroll") for (int k = 0; k < 2; ++k) dst[m][k] = *(const LAS bf16x8*)(lds + PG8_SA(b, h) + aoff + m * 2048 + k * 1024); } while (0)
; #define PG8_WAIT_V(n) asm volatile("s_waitcnt vmcnt(" #n ")" ::: "memory")
; #define PG8_WAIT_L(n) asm volatile("s_waitcnt lgkmcnt(" #n ")" ::: "memory")
; template <class Epi, class Sched>
; DI void gemm_phase(LAS unsigned char* lds, const int wv, const int lda, const int ldb, const Sched& S, const Epi& E) {
;     ...
;         const bool has_next = S.next(ui + 1, nxt);
;         const char* nA = has_next ? S.aptr(nxt) : cA; const char* nB = has_next ? S.bptr(nxt) : cB;
;         for (int t = 0; t < nt; t += 2) {
;             const bool last = (t == nt - 2);
;             const char* a1 = cA + (size_t)(t + 1) * kstep;
;             const char* a2 = last ? nA : cA + (size_t)(t + 2) * kstep; const char* b2 = last ? nB : cB + (size_t)(t + 2) * kstep;
;             const char* a3 = a2 + kstep; const char* b3 = b2 + kstep;
;             PG8_LDB(B0, 0, 0); PG8_LDB(B1, 0, 1); PG8_SCHED; PG8_LDA(At, 0, 0); PG8_STAGE(PG8_SA(1, 1), a1 + hstepA, voffA);
;             PG8_WAIT_V(8); PG8_WAIT_L(0); PG8_BAR; PG8_MMA(0, 0, At, B0); PG8_MMA(0, 1, At, B1); PG8_BAR; PG8_SCHED;
;             PG8_LDA(At, 0, 1); PG8_STAGE(PG8_SB(0, 0), b2, voffB); PG8_STAGE(PG8_SB(0, 1), b2 + hstepB, voffB); PG8_STAGE(PG8_SA(0, 0), a2, voffA);
;             PG8_WAIT_V(8); PG8_WAIT_L(0); PG8_BAR; PG8_MMA(1, 0, At, B0); PG8_MMA(1, 1, At, B1); PG8_BAR; PG8_SCHED;
.LBB0_1298:
	s_ashr_i32 s19, s18, 31
	s_lshl_b64 s[0:1], s[18:19], 20
	s_add_u32 s22, s33, s0
	s_addc_u32 s23, s38, s1
	s_and_b64 s[0:1], s[6:7], exec
	s_cselect_b32 s0, s23, s31
	s_cselect_b32 s1, s22, s30
	s_ashr_i32 s11, s10, 31
	s_lshl_b64 s[24:25], s[10:11], 20
	s_add_u32 s24, s39, s24
	s_addc_u32 s25, s40, s25
	s_and_b64 s[36:37], s[6:7], exec
	s_cselect_b32 s11, s25, s35
	s_cselect_b32 s15, s24, s34
	s_add_u32 s30, s30, 0x80080
	s_addc_u32 s31, s31, 0
	s_add_u32 s19, s34, 0x100
	s_addc_u32 s52, s35, 0
	s_mov_b32 s53, -2
	s_waitcnt lgkmcnt(0)
	s_add_u32 s34, s30, 0xfff80080
	s_addc_u32 s35, s31, -1
	s_add_i32 s54, 0, 0x10000
	s_cmp_eq_u32 s53, 28
	s_cselect_b32 s37, s0, s35
	s_cselect_b32 s36, s1, s34
	s_cselect_b32 s35, s11, s52
	s_cselect_b32 s34, s15, s19
	s_add_i32 s56, 0, 0x14000
	v_add_u32_e32 v150, s54, v155
	v_add_u32_e32 v172, s56, v155
	ds_read_b128 v[128:131], v150
	ds_read_b128 v[142:145], v150 offset:1024
	ds_read_b128 v[146:149], v150 offset:2048
	ds_read_b128 v[150:153], v150 offset:3072
	ds_read_b128 v[160:163], v172
	ds_read_b128 v[164:167], v172 offset:1024
	ds_read_b128 v[168:171], v172 offset:2048
	ds_read_b128 v[172:175], v172 offset:3072
	v_lshl_add_u64 v[216:217], s[30:31], 0, v[138:139]
	s_add_i32 m0, s27, 0xc000
	ds_read_b128 v[176:179], v159
	ds_read_b128 v[180:183], v159 offset:1024
	ds_read_b128 v[188:191], v159 offset:2048
	ds_read_b128 v[196:199], v159 offset:3072
	ds_read_b128 v[200:203], v159 offset:4096
	ds_read_b128 v[204:207], v159 offset:5120
	ds_read_b128 v[208:211], v159 offset:6144
	ds_read_b128 v[212:215], v159 offset:7168
	global_load_lds_dwordx4 v[216:217], off
	v_lshl_add_u64 v[216:217], s[30:31], 0, v[140:141]
	s_add_i32 m0, s27, 0xe000
	s_nop 0
	global_load_lds_dwordx4 v[216:217], off
	s_waitcnt vmcnt(8) lgkmcnt(0)
	s_barrier
	v_mfma_f32_16x16x32_bf16 v[124:127], v[128:131], v[176:179], 0
	v_mfma_f32_16x16x32_bf16 v[120:123], v[146:149], v[176:179], 0
	v_mfma_f32_16x16x32_bf16 v[108:111], v[128:131], v[188:191], 0
	v_mfma_f32_16x16x32_bf16 v[104:107], v[146:149], v[188:191], 0
	v_mfma_f32_16x16x32_bf16 v[96:99], v[128:131], v[200:203], 0
	v_mfma_f32_16x16x32_bf16 v[88:91], v[146:149], v[200:203], 0
	v_mfma_f32_16x16x32_bf16 v[80:83], v[128:131], v[208:211], 0
	v_mfma_f32_16x16x32_bf16 v[72:75], v[146:149], v[208:211], 0
	v_mfma_f32_16x16x32_bf16 v[124:127], v[142:145], v[180:183], v[124:127]
	v_mfma_f32_16x16x32_bf16 v[120:123], v[150:153], v[180:183], v[120:123]
	v_mfma_f32_16x16x32_bf16 v[108:111], v[142:145], v[196:199], v[108:111]
	v_mfma_f32_16x16x32_bf16 v[104:107], v[150:153], v[196:199], v[104:107]
	v_mfma_f32_16x16x32_bf16 v[96:99], v[142:145], v[204:207], v[96:99]
	v_mfma_f32_16x16x32_bf16 v[88:91], v[150:153], v[204:207], v[88:91]
	v_mfma_f32_16x16x32_bf16 v[80:83], v[142:145], v[212:215], v[80:83]
	v_mfma_f32_16x16x32_bf16 v[72:75], v[150:153], v[212:215], v[72:75]
	v_mfma_f32_16x16x32_bf16 v[116:119], v[160:163], v[176:179], 0
	v_mfma_f32_16x16x32_bf16 v[112:115], v[168:171], v[176:179], 0
	v_mfma_f32_16x16x32_bf16 v[100:103], v[160:163], v[188:191], 0
	v_mfma_f32_16x16x32_bf16 v[92:95], v[168:171], v[188:191], 0
	v_mfma_f32_16x16x32_bf16 v[84:87], v[160:163], v[200:203], 0
	v_mfma_f32_16x16x32_bf16 v[76:79], v[168:171], v[200:203], 0
	v_mfma_f32_16x16x32_bf16 v[68:71], v[160:163], v[208:211], 0
	v_mfma_f32_16x16x32_bf16 v[64:67], v[168:171], v[208:211], 0
	v_mfma_f32_16x16x32_bf16 v[116:119], v[164:167], v[180:183], v[116:119]
	v_mfma_f32_16x16x32_bf16 v[112:115], v[172:175], v[180:183], v[112:115]
	v_mfma_f32_16x16x32_bf16 v[100:103], v[164:167], v[196:199], v[100:103]
	v_mfma_f32_16x16x32_bf16 v[92:95], v[172:175], v[196:199], v[92:95]
	v_mfma_f32_16x16x32_bf16 v[84:87], v[164:167], v[204:207], v[84:87]
	v_mfma_f32_16x16x32_bf16 v[76:79], v[172:175], v[204:207], v[76:79]
	v_mfma_f32_16x16x32_bf16 v[68:71], v[164:167], v[212:215], v[68:71]
	v_mfma_f32_16x16x32_bf16 v[64:67], v[172:175], v[212:215], v[64:67]
	s_barrier
	s_add_i32 s54, s54, s41
	v_lshl_add_u64 v[216:217], s[34:35], 0, v[184:185]
	s_mov_b32 m0, s54
	ds_read_b128 v[176:179], v159 offset:16384
	ds_read_b128 v[180:183], v159 offset:17408
	ds_read_b128 v[188:191], v159 offset:18432
	ds_read_b128 v[196:199], v159 offset:19456
	ds_read_b128 v[200:203], v159 offset:20480
	ds_read_b128 v[204:207], v159 offset:21504
	ds_read_b128 v[208:211], v159 offset:22528
	ds_read_b128 v[212:215], v159 offset:23552
	global_load_lds_dwordx4 v[216:217], off
	s_add_i32 m0, s54, 0x2000
	s_add_u32 s54, s34, 0x80000
	v_lshl_add_u64 v[218:219], s[34:35], 0, v[136:137]
	s_addc_u32 s55, s35, 0
	s_add_i32 s56, s56, s41
	global_load_lds_dwordx4 v[218:219], off
	v_lshl_add_u64 v[220:221], s[54:55], 0, v[184:185]
	s_mov_b32 m0, s56
	v_lshl_add_u64 v[222:223], s[36:37], 0, v[134:135]
	global_load_lds_dwordx4 v[220:221], off
	v_lshl_add_u64 v[220:221], s[54:55], 0, v[136:137]
	s_add_i32 m0, s56, 0x2000
	s_nop 0
	global_load_lds_dwordx4 v[220:221], off
	v_lshl_add_u64 v[220:221], s[36:37], 0, v[132:133]
	s_mov_b32 m0, s27
	s_nop 0
	global_load_lds_dwordx4 v[220:221], off
	s_mov_b32 m0, s42
	s_nop 0
	global_load_lds_dwordx4 v[222:223], off
	s_waitcnt vmcnt(8) lgkmcnt(0)
	s_barrier
; #define PG8_STAGE(bufoff, gbase, voff) do { _Pragma("unroll") for (int _i = 0; _i < 2; ++_i) \
;         __builtin_amdgcn_global_load_lds((const unsigned*)((const char*)(gbase) + (voff)[_i]), (LAS unsigned*)(lds + (bufoff) + ldsw + _i * 8192), 16, 0, 0); } while (0)
; #define PG8_LDA(dst, b, h) do { _Pragma("unroll") for (int m = 0; m < 4; ++m) _Pragma("unroll") for (int k = 0; k < 2; ++k) dst[m][k] = *(const LAS bf16x8*)(lds + PG8_SA(b, h) + aoff + m * 2048 + k * 1024); } while (0)
; #define PG8_LDB(dst, b, h) do { _Pragma("unroll") for (int n = 0; n < 2; ++n) _Pragma("unroll") for (int k = 0; k < 2; ++k) dst[n][k] = *(const LAS bf16x8*)(lds + PG8_SB(b, h) + boff + n * 2048 + k * 1024); } while (0)
; #define PG8_MMA(ai, bj, At, Bt) do { __builtin_amdgcn_s_setprio(1); _Pragma("unroll") for (int m = 0; m < 4; ++m) _Pragma("unroll") for (int n = 0; n < 2; ++n) _Pragma("unroll") for (int k = 0; k < 2; ++k) \
;         acc[ai][bj][m][n] = __builtin_amdgcn_mfma_f32_16x16x32_bf16(Bt[n][k], At[m][k], acc[ai][bj][m][n], 0, 0, 0); __builtin_amdgcn_s_setprio(0); } while (0)
; #define PG8_WAIT_V(n) asm volatile("s_waitcnt vmcnt(" #n ")" ::: "memory")
; #define PG8_WAIT_L(n) asm volatile("s_waitcnt lgkmcnt(" #n ")" ::: "memory")
; #define PG8_BAR __builtin_amdgcn_s_barrier()
; #define PG8_SCHED __builtin_amdgcn_sched_barrier(0)
; template <class Epi, class Sched>
; DI void gemm_phase(LAS unsigned char* lds, const int wv, const int lda, const int ldb, const Sched& S, const Epi& E) {
;     ...
;             PG8_WAIT_V(8); PG8_WAIT_L(0); PG8_BAR; PG8_MMA(1, 0, At, B0); PG8_MMA(1, 1, At, B1); PG8_BAR; PG8_SCHED;
;             PG8_LDB(B0, 1, 0); PG8_LDB(B1, 1, 1); PG8_SCHED; PG8_LDA(At, 1, 0); PG8_STAGE(PG8_SA(0, 1), a2 + hstepA, voffA);
;             PG8_WAIT_V(8); PG8_WAIT_L(0); PG8_BAR; PG8_MMA(0, 0, At, B0); PG8_MMA(0, 1, At, B1); PG8_BAR; PG8_SCHED;
	v_mfma_f32_16x16x32_bf16 v[60:63], v[128:131], v[176:179], 0
	v_mfma_f32_16x16x32_bf16 v[56:59], v[146:149], v[176:179], 0
	v_mfma_f32_16x16x32_bf16 v[48:51], v[128:131], v[188:191], 0
	v_mfma_f32_16x16x32_bf16 v[40:43], v[146:149], v[188:191], 0
	v_mfma_f32_16x16x32_bf16 v[32:35], v[128:131], v[200:203], 0
	v_mfma_f32_16x16x32_bf16 v[24:27], v[146:149], v[200:203], 0
	v_mfma_f32_16x16x32_bf16 v[16:19], v[128:131], v[208:211], 0
	v_mfma_f32_16x16x32_bf16 v[8:11], v[146:149], v[208:211], 0
	v_mfma_f32_16x16x32_bf16 v[60:63], v[142:145], v[180:183], v[60:63]
	v_mfma_f32_16x16x32_bf16 v[56:59], v[150:153], v[180:183], v[56:59]
	v_mfma_f32_16x16x32_bf16 v[48:51], v[142:145], v[196:199], v[48:51]
	v_mfma_f32_16x16x32_bf16 v[40:43], v[150:153], v[196:199], v[40:43]
	v_mfma_f32_16x16x32_bf16 v[32:35], v[142:145], v[204:207], v[32:35]
	v_mfma_f32_16x16x32_bf16 v[24:27], v[150:153], v[204:207], v[24:27]
	v_mfma_f32_16x16x32_bf16 v[16:19], v[142:145], v[212:215], v[16:19]
	v_mfma_f32_16x16x32_bf16 v[8:11], v[150:153], v[212:215], v[8:11]
	v_mfma_f32_16x16x32_bf16 v[52:55], v[160:163], v[176:179], 0
	v_mfma_f32_16x16x32_bf16 v[44:47], v[168:171], v[176:179], 0
	v_mfma_f32_16x16x32_bf16 v[36:39], v[160:163], v[188:191], 0
	v_mfma_f32_16x16x32_bf16 v[28:31], v[168:171], v[188:191], 0
	v_mfma_f32_16x16x32_bf16 v[20:23], v[160:163], v[200:203], 0
	v_mfma_f32_16x16x32_bf16 v[12:15], v[168:171], v[200:203], 0
	v_mfma_f32_16x16x32_bf16 v[4:7], v[160:163], v[208:211], 0
	v_mfma_f32_16x16x32_bf16 v[0:3], v[168:171], v[208:211], 0
	v_mfma_f32_16x16x32_bf16 v[52:55], v[164:167], v[180:183], v[52:55]
	v_mfma_f32_16x16x32_bf16 v[44:47], v[172:175], v[180:183], v[44:47]
	v_mfma_f32_16x16x32_bf16 v[36:39], v[164:167], v[196:199], v[36:39]
	v_mfma_f32_16x16x32_bf16 v[28:31], v[172:175], v[196:199], v[28:31]
	v_mfma_f32_16x16x32_bf16 v[20:23], v[164:167], v[204:207], v[20:23]
	v_mfma_f32_16x16x32_bf16 v[12:15], v[172:175], v[204:207], v[12:15]
	v_mfma_f32_16x16x32_bf16 v[4:7], v[164:167], v[212:215], v[4:7]
	v_mfma_f32_16x16x32_bf16 v[0:3], v[172:175], v[212:215], v[0:3]
	s_barrier
	s_add_i32 s54, 0, 0x18000
	s_add_i32 s55, 0, 0x1c000
	v_add_u32_e32 v150, s54, v155
	v_add_u32_e32 v172, s55, v155
	ds_read_b128 v[128:131], v150
	ds_read_b128 v[142:145], v150 offset:1024
	ds_read_b128 v[146:149], v150 offset:2048
	ds_read_b128 v[150:153], v150 offset:3072
	ds_read_b128 v[160:163], v172
	ds_read_b128 v[164:167], v172 offset:1024
	ds_read_b128 v[168:171], v172 offset:2048
	ds_read_b128 v[172:175], v172 offset:3072
	s_add_u32 s36, s36, 0x80000
	s_addc_u32 s37, s37, 0
	s_mov_b32 m0, s43
	v_lshl_add_u64 v[234:235], s[36:37], 0, v[132:133]
	ds_read_b128 v[176:179], v159 offset:32768
	ds_read_b128 v[180:183], v159 offset:33792
	ds_read_b128 v[188:191], v159 offset:34816
	ds_read_b128 v[196:199], v159 offset:35840
	ds_read_b128 v[200:203], v159 offset:36864
	ds_read_b128 v[204:207], v159 offset:37888
	ds_read_b128 v[208:211], v159 offset:38912
	ds_read_b128 v[212:215], v159 offset:39936
	global_load_lds_dwordx4 v[234:235], off
	v_lshl_add_u64 v[234:235], s[36:37], 0, v[134:135]
	s_mov_b32 m0, s44
	s_nop 0
	global_load_lds_dwordx4 v[234:235], off
	s_waitcnt vmcnt(8) lgkmcnt(0)
	s_barrier
	v_mfma_f32_16x16x32_bf16 v[124:127], v[128:131], v[176:179], v[124:127]
	v_mfma_f32_16x16x32_bf16 v[120:123], v[146:149], v[176:179], v[120:123]
	v_mfma_f32_16x16x32_bf16 v[108:111], v[128:131], v[188:191], v[108:111]
	v_mfma_f32_16x16x32_bf16 v[104:107], v[146:149], v[188:191], v[104:107]
	v_mfma_f32_16x16x32_bf16 v[96:99], v[128:131], v[200:203], v[96:99]
	v_mfma_f32_16x16x32_bf16 v[88:91], v[146:149], v[200:203], v[88:91]
	v_mfma_f32_16x16x32_bf16 v[80:83], v[128:131], v[208:211], v[80:83]
	v_mfma_f32_16x16x32_bf16 v[72:75], v[146:149], v[208:211], v[72:75]
	v_mfma_f32_16x16x32_bf16 v[124:127], v[142:145], v[180:183], v[124:127]
	v_mfma_f32_16x16x32_bf16 v[120:123], v[150:153], v[180:183], v[120:123]
	v_mfma_f32_16x16x32_bf16 v[108:111], v[142:145], v[196:199], v[108:111]
	v_mfma_f32_16x16x32_bf16 v[104:107], v[150:153], v[196:199], v[104:107]
	v_mfma_f32_16x16x32_bf16 v[96:99], v[142:145], v[204:207], v[96:99]
	v_mfma_f32_16x16x32_bf16 v[88:91], v[150:153], v[204:207], v[88:91]
	v_mfma_f32_16x16x32_bf16 v[80:83], v[142:145], v[212:215], v[80:83]
	v_mfma_f32_16x16x32_bf16 v[72:75], v[150:153], v[212:215], v[72:75]
	v_mfma_f32_16x16x32_bf16 v[116:119], v[160:163], v[176:179], v[116:119]
	v_mfma_f32_16x16x32_bf16 v[112:115], v[168:171], v[176:179], v[112:115]
	v_mfma_f32_16x16x32_bf16 v[100:103], v[160:163], v[188:191], v[100:103]
	v_mfma_f32_16x16x32_bf16 v[92:95], v[168:171], v[188:191], v[92:95]
	v_mfma_f32_16x16x32_bf16 v[84:87], v[160:163], v[200:203], v[84:87]
	v_mfma_f32_16x16x32_bf16 v[76:79], v[168:171], v[200:203], v[76:79]
	v_mfma_f32_16x16x32_bf16 v[68:71], v[160:163], v[208:211], v[68:71]
	v_mfma_f32_16x16x32_bf16 v[64:67], v[168:171], v[208:211], v[64:67]
	v_mfma_f32_16x16x32_bf16 v[116:119], v[164:167], v[180:183], v[116:119]
	v_mfma_f32_16x16x32_bf16 v[112:115], v[172:175], v[180:183], v[112:115]
	v_mfma_f32_16x16x32_bf16 v[100:103], v[164:167], v[196:199], v[100:103]
	v_mfma_f32_16x16x32_bf16 v[92:95], v[172:175], v[196:199], v[92:95]
	v_mfma_f32_16x16x32_bf16 v[84:87], v[164:167], v[204:207], v[84:87]
	v_mfma_f32_16x16x32_bf16 v[76:79], v[172:175], v[204:207], v[76:79]
	v_mfma_f32_16x16x32_bf16 v[68:71], v[164:167], v[212:215], v[68:71]
	v_mfma_f32_16x16x32_bf16 v[64:67], v[172:175], v[212:215], v[64:67]
	s_barrier
; #define PG8_STAGE(bufoff, gbase, voff) do { _Pragma("unroll") for (int _i = 0; _i < 2; ++_i) \
;         __builtin_amdgcn_global_load_lds((const unsigned*)((const char*)(gbase) + (voff)[_i]), (LAS unsigned*)(lds + (bufoff) + ldsw + _i * 8192), 16, 0, 0); } while (0)
; #define PG8_LDA(dst, b, h) do { _Pragma("unroll") for (int m = 0; m < 4; ++m) _Pragma("unroll") for (int k = 0; k < 2; ++k) dst[m][k] = *(const LAS bf16x8*)(lds + PG8_SA(b, h) + aoff + m * 2048 + k * 1024); } while (0)
; #define PG8_MMA(ai, bj, At, Bt) do { __builtin_amdgcn_s_setprio(1); _Pragma("unroll") for (int m = 0; m < 4; ++m) _Pragma("unroll") for (int n = 0; n < 2; ++n) _Pragma("unroll") for (int k = 0; k < 2; ++k) \
;         acc[ai][bj][m][n] = __builtin_amdgcn_mfma_f32_16x16x32_bf16(Bt[n][k], At[m][k], acc[ai][bj][m][n], 0, 0, 0); __builtin_amdgcn_s_setprio(0); } while (0)
; #define PG8_WAIT_V(n) asm volatile("s_waitcnt vmcnt(" #n ")" ::: "memory")
; #define PG8_WAIT_L(n) asm volatile("s_waitcnt lgkmcnt(" #n ")" ::: "memory")
; #define PG8_BAR __builtin_amdgcn_s_barrier()
; #define PG8_SCHED __builtin_amdgcn_sched_barrier(0)
; template <class Epi, class Sched>
; DI void gemm_phase(LAS unsigned char* lds, const int wv, const int lda, const int ldb, const Sched& S, const Epi& E) {
;     ...
;             PG8_LDA(At, 1, 1); PG8_STAGE(PG8_SB(1, 0), b3, voffB); PG8_STAGE(PG8_SB(1, 1), b3 + hstepB, voffB); PG8_STAGE(PG8_SA(1, 0), a3, voffA);
;             PG8_WAIT_V(8); PG8_WAIT_L(0); PG8_BAR; PG8_MMA(1, 0, At, B0); PG8_MMA(1, 1, At, B1); PG8_BAR; PG8_SCHED;
;         }
	s_add_i32 s36, s54, s41
	v_lshl_add_u64 v[216:217], v[216:217], 0, s[28:29]
	s_mov_b32 m0, s36
	ds_read_b128 v[176:179], v159 offset:49152
	ds_read_b128 v[180:183], v159 offset:50176
	ds_read_b128 v[188:191], v159 offset:51200
	ds_read_b128 v[196:199], v159 offset:52224
	ds_read_b128 v[200:203], v159 offset:53248
	ds_read_b128 v[204:207], v159 offset:54272
	ds_read_b128 v[208:211], v159 offset:55296
	ds_read_b128 v[212:215], v159 offset:56320
	global_load_lds_dwordx4 v[216:217], off
	s_add_i32 m0, s36, 0x2000
	s_add_u32 s34, s34, 0x80080
	v_lshl_add_u64 v[216:217], v[218:219], 0, s[28:29]
	s_addc_u32 s35, s35, 0
	s_add_i32 s36, s55, s41
	global_load_lds_dwordx4 v[216:217], off
	v_lshl_add_u64 v[216:217], s[34:35], 0, v[184:185]
	s_mov_b32 m0, s36
	s_nop 0
	global_load_lds_dwordx4 v[216:217], off
	v_lshl_add_u64 v[216:217], s[34:35], 0, v[136:137]
	s_add_i32 m0, s36, 0x2000
	s_nop 0
	global_load_lds_dwordx4 v[216:217], off
	v_lshl_add_u64 v[216:217], v[220:221], 0, s[28:29]
	s_mov_b32 m0, s45
	s_nop 0
	global_load_lds_dwordx4 v[216:217], off
	v_lshl_add_u64 v[216:217], v[222:223], 0, s[28:29]
	s_mov_b32 m0, s46
	s_nop 0
	global_load_lds_dwordx4 v[216:217], off
	s_waitcnt vmcnt(8) lgkmcnt(0)
	s_barrier
	v_mfma_f32_16x16x32_bf16 v[60:63], v[128:131], v[176:179], v[60:63]
	v_mfma_f32_16x16x32_bf16 v[56:59], v[146:149], v[176:179], v[56:59]
	v_mfma_f32_16x16x32_bf16 v[48:51], v[128:131], v[188:191], v[48:51]
	v_mfma_f32_16x16x32_bf16 v[40:43], v[146:149], v[188:191], v[40:43]
	v_mfma_f32_16x16x32_bf16 v[32:35], v[128:131], v[200:203], v[32:35]
	v_mfma_f32_16x16x32_bf16 v[24:27], v[146:149], v[200:203], v[24:27]
	v_mfma_f32_16x16x32_bf16 v[16:19], v[128:131], v[208:211], v[16:19]
	v_mfma_f32_16x16x32_bf16 v[8:11], v[146:149], v[208:211], v[8:11]
	v_mfma_f32_16x16x32_bf16 v[60:63], v[142:145], v[180:183], v[60:63]
	v_mfma_f32_16x16x32_bf16 v[56:59], v[150:153], v[180:183], v[56:59]
	v_mfma_f32_16x16x32_bf16 v[48:51], v[142:145], v[196:199], v[48:51]
	v_mfma_f32_16x16x32_bf16 v[40:43], v[150:153], v[196:199], v[40:43]
	v_mfma_f32_16x16x32_bf16 v[32:35], v[142:145], v[204:207], v[32:35]
	v_mfma_f32_16x16x32_bf16 v[24:27], v[150:153], v[204:207], v[24:27]
	v_mfma_f32_16x16x32_bf16 v[16:19], v[142:145], v[212:215], v[16:19]
	v_mfma_f32_16x16x32_bf16 v[8:11], v[150:153], v[212:215], v[8:11]
	v_mfma_f32_16x16x32_bf16 v[52:55], v[160:163], v[176:179], v[52:55]
	v_mfma_f32_16x16x32_bf16 v[44:47], v[168:171], v[176:179], v[44:47]
	v_mfma_f32_16x16x32_bf16 v[36:39], v[160:163], v[188:191], v[36:39]
	v_mfma_f32_16x16x32_bf16 v[28:31], v[168:171], v[188:191], v[28:31]
	v_mfma_f32_16x16x32_bf16 v[20:23], v[160:163], v[200:203], v[20:23]
	v_mfma_f32_16x16x32_bf16 v[12:15], v[168:171], v[200:203], v[12:15]
	v_mfma_f32_16x16x32_bf16 v[4:7], v[160:163], v[208:211], v[4:7]
	v_mfma_f32_16x16x32_bf16 v[0:3], v[168:171], v[208:211], v[0:3]
	v_mfma_f32_16x16x32_bf16 v[52:55], v[164:167], v[180:183], v[52:55]
	v_mfma_f32_16x16x32_bf16 v[44:47], v[172:175], v[180:183], v[44:47]
	v_mfma_f32_16x16x32_bf16 v[36:39], v[164:167], v[196:199], v[36:39]
	v_mfma_f32_16x16x32_bf16 v[28:31], v[172:175], v[196:199], v[28:31]
	v_mfma_f32_16x16x32_bf16 v[20:23], v[164:167], v[204:207], v[20:23]
	v_mfma_f32_16x16x32_bf16 v[12:15], v[172:175], v[204:207], v[12:15]
	v_mfma_f32_16x16x32_bf16 v[4:7], v[164:167], v[212:215], v[4:7]
	v_mfma_f32_16x16x32_bf16 v[0:3], v[172:175], v[212:215], v[0:3]
	s_barrier
	s_add_i32 s53, s53, 2
	s_add_u32 s30, s30, 0x100
	s_addc_u32 s31, s31, 0
	s_add_u32 s19, s19, 0x100
	s_addc_u32 s52, s52, 0

;     DI bool next(int i, Unit& u) const { const long L = (long)i * G + c; if (L >= T.nwg) return false; T.map((int)L, u.pm, u.pn); u.seg = 0; return true; }
;     DI bool next(int i, Unit& u) const { const int ti = i / 3; const long L = (long)ti * G + c; if (L >= T.nwg) return false; T.map((int)L, u.pm, u.pn); u.seg = i - 3 * ti; return true; }
;     DI const char* aptr(const Unit& u) const { return A + (size_t)u.pm * ta + (size_t)kofs(u.seg) * 2; }
;     DI const char* bptr(const Unit& u) const { return B + (size_t)u.pn * tb + (size_t)kofs(u.seg) * 2; }
; #define PG8_STAGE(bufoff, gbase, voff) do { _Pragma("unroll") for (int _i = 0; _i < 2; ++_i) \
;         __builtin_amdgcn_global_load_lds((const unsigned*)((const char*)(gbase) + (voff)[_i]), (LAS unsigned*)(lds + (bufoff) + ldsw + _i * 8192), 16, 0, 0); } while (0)
; #define PG8_LDA(dst, b, h) do { _Pragma("unroll") for (int m = 0; m < 4; ++m) _Pragma("unroll") for (int k = 0; k < 2; ++k) dst[m][k] = *(const LAS bf16x8*)(lds + PG8_SA(b, h) + aoff + m * 2048 + k * 1024); } while (0)
; #define PG8_WAIT_V(n) asm volatile("s_waitcnt vmcnt(" #n ")" ::: "memory")
; #define PG8_WAIT_L(n) asm volatile("s_waitcnt lgkmcnt(" #n ")" ::: "memory")
; template <class Epi, class Sched>
; DI void gemm_phase(LAS unsigned char* lds, const int wv, const int lda, const int ldb, const Sched& S, const Epi& E) {
;     ...
;         const bool has_next = S.next(ui + 1, nxt);
;         const char* nA = has_next ? S.aptr(nxt) : cA; const char* nB = has_next ? S.bptr(nxt) : cB;
;         for (int t = 0; t < nt; t += 2) {
;             const bool last = (t == nt - 2);
;             const char* a1 = cA + (size_t)(t + 1) * kstep;
;             const char* a2 = last ? nA : cA + (size_t)(t + 2) * kstep; const char* b2 = last ? nB : cB + (size_t)(t + 2) * kstep;
;             const char* a3 = a2 + kstep; const char* b3 = b2 + kstep;
;             PG8_LDB(B0, 0, 0); PG8_LDB(B1, 0, 1); PG8_SCHED; PG8_LDA(At, 0, 0); PG8_STAGE(PG8_SA(1, 1), a1 + hstepA, voffA);
;             PG8_WAIT_V(8); PG8_WAIT_L(0); PG8_BAR; PG8_MMA(0, 0, At, B0); PG8_MMA(0, 1, At, B1); PG8_BAR; PG8_SCHED;
;             PG8_LDA(At, 0, 1); PG8_STAGE(PG8_SB(0, 0), b2, voffB); PG8_STAGE(PG8_SB(0, 1), b2 + hstepB, voffB); PG8_STAGE(PG8_SA(0, 0), a2, voffA);
;             PG8_WAIT_V(8); PG8_WAIT_L(0); PG8_BAR; PG8_MMA(1, 0, At, B0); PG8_MMA(1, 1, At, B1); PG8_BAR; PG8_SCHED;
.LBB0_1396:
	s_ashr_i32 s15, s14, 31
	s_lshl_b64 s[0:1], s[14:15], 20
	s_add_u32 s18, s8, s0
	s_addc_u32 s19, s9, s1
	s_and_b64 s[0:1], s[4:5], exec
	s_cselect_b32 s0, s19, s27
	s_cselect_b32 s1, s18, s26
	s_ashr_i32 s13, s12, 31
	s_lshl_b64 s[22:23], s[12:13], 20
	s_add_u32 s22, s36, s22
	s_addc_u32 s23, s37, s23
	s_and_b64 s[34:35], s[4:5], exec
	s_cselect_b32 s13, s23, s31
	s_cselect_b32 s15, s22, s30
	s_add_u32 s26, s26, 0x80080
	s_addc_u32 s27, s27, 0
	s_add_u32 s48, s30, 0x100
	s_addc_u32 s49, s31, 0
	s_mov_b32 s50, -2
	s_add_u32 s30, s26, 0xfff80080
	s_addc_u32 s31, s27, -1
	s_add_i32 s51, 0, 0x10000
	s_cmp_eq_u32 s50, 28
	s_cselect_b32 s35, s0, s31
	s_cselect_b32 s34, s1, s30
	v_add_u32_e32 v142, s51, v145
	s_cselect_b32 s31, s13, s49
	s_cselect_b32 s30, s15, s48
	s_add_i32 s54, 0, 0x14000
	ds_read_b128 v[138:141], v142
	ds_read_b128 v[148:151], v142 offset:1024
	ds_read_b128 v[152:155], v142 offset:2048
	ds_read_b128 v[156:159], v142 offset:3072
	v_add_u32_e32 v142, s54, v145
	ds_read_b128 v[160:163], v142
	ds_read_b128 v[164:167], v142 offset:1024
	ds_read_b128 v[168:171], v142 offset:2048
	ds_read_b128 v[172:175], v142 offset:3072
	v_lshl_add_u64 v[142:143], s[26:27], 0, v[134:135]
	s_add_i32 m0, s25, 0xc000
	ds_read_b128 v[176:179], v147
	ds_read_b128 v[180:183], v147 offset:1024
	ds_read_b128 v[188:191], v147 offset:2048
	ds_read_b128 v[196:199], v147 offset:3072
	ds_read_b128 v[200:203], v147 offset:4096
	ds_read_b128 v[204:207], v147 offset:5120
	ds_read_b128 v[208:211], v147 offset:6144
	ds_read_b128 v[212:215], v147 offset:7168
	global_load_lds_dwordx4 v[142:143], off
	v_lshl_add_u64 v[142:143], s[26:27], 0, v[136:137]
	s_add_i32 m0, s25, 0xe000
	s_nop 0
	global_load_lds_dwordx4 v[142:143], off
	s_waitcnt vmcnt(8) lgkmcnt(0)
	s_barrier
	v_mfma_f32_16x16x32_bf16 v[124:127], v[138:141], v[176:179], 0
	v_mfma_f32_16x16x32_bf16 v[120:123], v[152:155], v[176:179], 0
	v_mfma_f32_16x16x32_bf16 v[108:111], v[138:141], v[188:191], 0
	v_mfma_f32_16x16x32_bf16 v[104:107], v[152:155], v[188:191], 0
	v_mfma_f32_16x16x32_bf16 v[92:95], v[138:141], v[200:203], 0
	v_mfma_f32_16x16x32_bf16 v[88:91], v[152:155], v[200:203], 0
	v_mfma_f32_16x16x32_bf16 v[76:79], v[138:141], v[208:211], 0
	v_mfma_f32_16x16x32_bf16 v[72:75], v[152:155], v[208:211], 0
	v_mfma_f32_16x16x32_bf16 v[124:127], v[148:151], v[180:183], v[124:127]
	v_mfma_f32_16x16x32_bf16 v[120:123], v[156:159], v[180:183], v[120:123]
	v_mfma_f32_16x16x32_bf16 v[108:111], v[148:151], v[196:199], v[108:111]
	v_mfma_f32_16x16x32_bf16 v[104:107], v[156:159], v[196:199], v[104:107]
	v_mfma_f32_16x16x32_bf16 v[92:95], v[148:151], v[204:207], v[92:95]
	v_mfma_f32_16x16x32_bf16 v[88:91], v[156:159], v[204:207], v[88:91]
	v_mfma_f32_16x16x32_bf16 v[76:79], v[148:151], v[212:215], v[76:79]
	v_mfma_f32_16x16x32_bf16 v[72:75], v[156:159], v[212:215], v[72:75]
	v_mfma_f32_16x16x32_bf16 v[116:119], v[160:163], v[176:179], 0
	v_mfma_f32_16x16x32_bf16 v[112:115], v[168:171], v[176:179], 0
	v_mfma_f32_16x16x32_bf16 v[100:103], v[160:163], v[188:191], 0
	v_mfma_f32_16x16x32_bf16 v[96:99], v[168:171], v[188:191], 0
	v_mfma_f32_16x16x32_bf16 v[84:87], v[160:163], v[200:203], 0
	v_mfma_f32_16x16x32_bf16 v[80:83], v[168:171], v[200:203], 0
	v_mfma_f32_16x16x32_bf16 v[68:71], v[160:163], v[208:211], 0
	v_mfma_f32_16x16x32_bf16 v[64:67], v[168:171], v[208:211], 0
	v_mfma_f32_16x16x32_bf16 v[116:119], v[164:167], v[180:183], v[116:119]
	v_mfma_f32_16x16x32_bf16 v[112:115], v[172:175], v[180:183], v[112:115]
	v_mfma_f32_16x16x32_bf16 v[100:103], v[164:167], v[196:199], v[100:103]
	v_mfma_f32_16x16x32_bf16 v[96:99], v[172:175], v[196:199], v[96:99]
	v_mfma_f32_16x16x32_bf16 v[84:87], v[164:167], v[204:207], v[84:87]
	v_mfma_f32_16x16x32_bf16 v[80:83], v[172:175], v[204:207], v[80:83]
	v_mfma_f32_16x16x32_bf16 v[68:71], v[164:167], v[212:215], v[68:71]
	v_mfma_f32_16x16x32_bf16 v[64:67], v[172:175], v[212:215], v[64:67]
	s_barrier
	s_add_i32 s51, s51, s38
	v_lshl_add_u64 v[142:143], s[30:31], 0, v[184:185]
	s_mov_b32 m0, s51
	ds_read_b128 v[176:179], v147 offset:16384
	ds_read_b128 v[180:183], v147 offset:17408
	ds_read_b128 v[188:191], v147 offset:18432
	ds_read_b128 v[196:199], v147 offset:19456
	ds_read_b128 v[200:203], v147 offset:20480
	ds_read_b128 v[204:207], v147 offset:21504
	ds_read_b128 v[208:211], v147 offset:22528
	ds_read_b128 v[212:215], v147 offset:23552
	global_load_lds_dwordx4 v[142:143], off
	s_add_i32 m0, s51, 0x2000
	s_add_u32 s52, s30, 0x80000
	v_lshl_add_u64 v[216:217], s[30:31], 0, v[132:133]
	s_addc_u32 s53, s31, 0
	s_add_i32 s51, s54, s38
	global_load_lds_dwordx4 v[216:217], off
	v_lshl_add_u64 v[218:219], s[52:53], 0, v[184:185]
	s_mov_b32 m0, s51
	v_lshl_add_u64 v[220:221], s[34:35], 0, v[130:131]
	global_load_lds_dwordx4 v[218:219], off
	v_lshl_add_u64 v[218:219], s[52:53], 0, v[132:133]
	s_add_i32 m0, s51, 0x2000
	s_nop 0
	global_load_lds_dwordx4 v[218:219], off
	v_lshl_add_u64 v[218:219], s[34:35], 0, v[128:129]
	s_mov_b32 m0, s25
	s_nop 0
	global_load_lds_dwordx4 v[218:219], off
	s_mov_b32 m0, s39
	s_nop 0
	global_load_lds_dwordx4 v[220:221], off
	s_waitcnt vmcnt(8) lgkmcnt(0)
	s_barrier
; #define PG8_STAGE(bufoff, gbase, voff) do { _Pragma("unroll") for (int _i = 0; _i < 2; ++_i) \
;         __builtin_amdgcn_global_load_lds((const unsigned*)((const char*)(gbase) + (voff)[_i]), (LAS unsigned*)(lds + (bufoff) + ldsw + _i * 8192), 16, 0, 0); } while (0)
; #define PG8_LDA(dst, b, h) do { _Pragma("unroll") for (int m = 0; m < 4; ++m) _Pragma("unroll") for (int k = 0; k < 2; ++k) dst[m][k] = *(const LAS bf16x8*)(lds + PG8_SA(b, h) + aoff + m * 2048 + k * 1024); } while (0)
; #define PG8_LDB(dst, b, h) do { _Pragma("unroll") for (int n = 0; n < 2; ++n) _Pragma("unroll") for (int k = 0; k < 2; ++k) dst[n][k] = *(const LAS bf16x8*)(lds + PG8_SB(b, h) + boff + n * 2048 + k * 1024); } while (0)
; #define PG8_MMA(ai, bj, At, Bt) do { __builtin_amdgcn_s_setprio(1); _Pragma("unroll") for (int m = 0; m < 4; ++m) _Pragma("unroll") for (int n = 0; n < 2; ++n) _Pragma("unroll") for (int k = 0; k < 2; ++k) \
;         acc[ai][bj][m][n] = __builtin_amdgcn_mfma_f32_16x16x32_bf16(Bt[n][k], At[m][k], acc[ai][bj][m][n], 0, 0, 0); __builtin_amdgcn_s_setprio(0); } while (0)
; #define PG8_WAIT_V(n) asm volatile("s_waitcnt vmcnt(" #n ")" ::: "memory")
; #define PG8_WAIT_L(n) asm volatile("s_waitcnt lgkmcnt(" #n ")" ::: "memory")
; #define PG8_BAR __builtin_amdgcn_s_barrier()
; #define PG8_SCHED __builtin_amdgcn_sched_barrier(0)
; template <class Epi, class Sched>
; DI void gemm_phase(LAS unsigned char* lds, const int wv, const int lda, const int ldb, const Sched& S, const Epi& E) {
;     ...
;             PG8_WAIT_V(8); PG8_WAIT_L(0); PG8_BAR; PG8_MMA(1, 0, At, B0); PG8_MMA(1, 1, At, B1); PG8_BAR; PG8_SCHED;
;             PG8_LDB(B0, 1, 0); PG8_LDB(B1, 1, 1); PG8_SCHED; PG8_LDA(At, 1, 0); PG8_STAGE(PG8_SA(0, 1), a2 + hstepA, voffA);
;             PG8_WAIT_V(8); PG8_WAIT_L(0); PG8_BAR; PG8_MMA(0, 0, At, B0); PG8_MMA(0, 1, At, B1); PG8_BAR; PG8_SCHED;
	v_mfma_f32_16x16x32_bf16 v[60:63], v[138:141], v[176:179], 0
	v_mfma_f32_16x16x32_bf16 v[56:59], v[152:155], v[176:179], 0
	v_mfma_f32_16x16x32_bf16 v[44:47], v[138:141], v[188:191], 0
	v_mfma_f32_16x16x32_bf16 v[40:43], v[152:155], v[188:191], 0
	v_mfma_f32_16x16x32_bf16 v[28:31], v[138:141], v[200:203], 0
	v_mfma_f32_16x16x32_bf16 v[24:27], v[152:155], v[200:203], 0
	v_mfma_f32_16x16x32_bf16 v[12:15], v[138:141], v[208:211], 0
	v_mfma_f32_16x16x32_bf16 v[8:11], v[152:155], v[208:211], 0
	v_mfma_f32_16x16x32_bf16 v[60:63], v[148:151], v[180:183], v[60:63]
	v_mfma_f32_16x16x32_bf16 v[56:59], v[156:159], v[180:183], v[56:59]
	v_mfma_f32_16x16x32_bf16 v[44:47], v[148:151], v[196:199], v[44:47]
	v_mfma_f32_16x16x32_bf16 v[40:43], v[156:159], v[196:199], v[40:43]
	v_mfma_f32_16x16x32_bf16 v[28:31], v[148:151], v[204:207], v[28:31]
	v_mfma_f32_16x16x32_bf16 v[24:27], v[156:159], v[204:207], v[24:27]
	v_mfma_f32_16x16x32_bf16 v[12:15], v[148:151], v[212:215], v[12:15]
	v_mfma_f32_16x16x32_bf16 v[8:11], v[156:159], v[212:215], v[8:11]
	v_mfma_f32_16x16x32_bf16 v[52:55], v[160:163], v[176:179], 0
	v_mfma_f32_16x16x32_bf16 v[48:51], v[168:171], v[176:179], 0
	v_mfma_f32_16x16x32_bf16 v[36:39], v[160:163], v[188:191], 0
	v_mfma_f32_16x16x32_bf16 v[32:35], v[168:171], v[188:191], 0
	v_mfma_f32_16x16x32_bf16 v[20:23], v[160:163], v[200:203], 0
	v_mfma_f32_16x16x32_bf16 v[16:19], v[168:171], v[200:203], 0
	v_mfma_f32_16x16x32_bf16 v[4:7], v[160:163], v[208:211], 0
	v_mfma_f32_16x16x32_bf16 v[0:3], v[168:171], v[208:211], 0
	v_mfma_f32_16x16x32_bf16 v[52:55], v[164:167], v[180:183], v[52:55]
	v_mfma_f32_16x16x32_bf16 v[48:51], v[172:175], v[180:183], v[48:51]
	v_mfma_f32_16x16x32_bf16 v[36:39], v[164:167], v[196:199], v[36:39]
	v_mfma_f32_16x16x32_bf16 v[32:35], v[172:175], v[196:199], v[32:35]
	v_mfma_f32_16x16x32_bf16 v[20:23], v[164:167], v[204:207], v[20:23]
	v_mfma_f32_16x16x32_bf16 v[16:19], v[172:175], v[204:207], v[16:19]
	v_mfma_f32_16x16x32_bf16 v[4:7], v[164:167], v[212:215], v[4:7]
	v_mfma_f32_16x16x32_bf16 v[0:3], v[172:175], v[212:215], v[0:3]
	s_barrier
	s_add_i32 s51, 0, 0x18000
	s_add_i32 s52, 0, 0x1c000
	v_add_u32_e32 v156, s51, v145
	v_add_u32_e32 v172, s52, v145
	ds_read_b128 v[138:141], v156
	ds_read_b128 v[148:151], v156 offset:1024
	ds_read_b128 v[152:155], v156 offset:2048
	ds_read_b128 v[156:159], v156 offset:3072
	ds_read_b128 v[160:163], v172
	ds_read_b128 v[164:167], v172 offset:1024
	ds_read_b128 v[168:171], v172 offset:2048
	ds_read_b128 v[172:175], v172 offset:3072
	s_add_u32 s34, s34, 0x80000
	s_addc_u32 s35, s35, 0
	s_mov_b32 m0, s40
	v_lshl_add_u64 v[222:223], s[34:35], 0, v[128:129]
	ds_read_b128 v[176:179], v147 offset:32768
	ds_read_b128 v[180:183], v147 offset:33792
	ds_read_b128 v[188:191], v147 offset:34816
	ds_read_b128 v[196:199], v147 offset:35840
	ds_read_b128 v[200:203], v147 offset:36864
	ds_read_b128 v[204:207], v147 offset:37888
	ds_read_b128 v[208:211], v147 offset:38912
	ds_read_b128 v[212:215], v147 offset:39936
	global_load_lds_dwordx4 v[222:223], off
	v_lshl_add_u64 v[222:223], s[34:35], 0, v[130:131]
	s_mov_b32 m0, s41
	s_nop 0
	global_load_lds_dwordx4 v[222:223], off
	s_waitcnt vmcnt(8) lgkmcnt(0)
	s_barrier
	v_mfma_f32_16x16x32_bf16 v[124:127], v[138:141], v[176:179], v[124:127]
	v_mfma_f32_16x16x32_bf16 v[120:123], v[152:155], v[176:179], v[120:123]
	v_mfma_f32_16x16x32_bf16 v[108:111], v[138:141], v[188:191], v[108:111]
	v_mfma_f32_16x16x32_bf16 v[104:107], v[152:155], v[188:191], v[104:107]
	v_mfma_f32_16x16x32_bf16 v[92:95], v[138:141], v[200:203], v[92:95]
	v_mfma_f32_16x16x32_bf16 v[88:91], v[152:155], v[200:203], v[88:91]
	v_mfma_f32_16x16x32_bf16 v[76:79], v[138:141], v[208:211], v[76:79]
	v_mfma_f32_16x16x32_bf16 v[72:75], v[152:155], v[208:211], v[72:75]
	v_mfma_f32_16x16x32_bf16 v[124:127], v[148:151], v[180:183], v[124:127]
	v_mfma_f32_16x16x32_bf16 v[120:123], v[156:159], v[180:183], v[120:123]
	v_mfma_f32_16x16x32_bf16 v[108:111], v[148:151], v[196:199], v[108:111]
	v_mfma_f32_16x16x32_bf16 v[104:107], v[156:159], v[196:199], v[104:107]
	v_mfma_f32_16x16x32_bf16 v[92:95], v[148:151], v[204:207], v[92:95]
	v_mfma_f32_16x16x32_bf16 v[88:91], v[156:159], v[204:207], v[88:91]
	v_mfma_f32_16x16x32_bf16 v[76:79], v[148:151], v[212:215], v[76:79]
	v_mfma_f32_16x16x32_bf16 v[72:75], v[156:159], v[212:215], v[72:75]
	v_mfma_f32_16x16x32_bf16 v[116:119], v[160:163], v[176:179], v[116:119]
	v_mfma_f32_16x16x32_bf16 v[112:115], v[168:171], v[176:179], v[112:115]
	v_mfma_f32_16x16x32_bf16 v[100:103], v[160:163], v[188:191], v[100:103]
	v_mfma_f32_16x16x32_bf16 v[96:99], v[168:171], v[188:191], v[96:99]
	v_mfma_f32_16x16x32_bf16 v[84:87], v[160:163], v[200:203], v[84:87]
	v_mfma_f32_16x16x32_bf16 v[80:83], v[168:171], v[200:203], v[80:83]
	v_mfma_f32_16x16x32_bf16 v[68:71], v[160:163], v[208:211], v[68:71]
	v_mfma_f32_16x16x32_bf16 v[64:67], v[168:171], v[208:211], v[64:67]
	v_mfma_f32_16x16x32_bf16 v[116:119], v[164:167], v[180:183], v[116:119]
	v_mfma_f32_16x16x32_bf16 v[112:115], v[172:175], v[180:183], v[112:115]
	v_mfma_f32_16x16x32_bf16 v[100:103], v[164:167], v[196:199], v[100:103]
	v_mfma_f32_16x16x32_bf16 v[96:99], v[172:175], v[196:199], v[96:99]
	v_mfma_f32_16x16x32_bf16 v[84:87], v[164:167], v[204:207], v[84:87]
	v_mfma_f32_16x16x32_bf16 v[80:83], v[172:175], v[204:207], v[80:83]
	v_mfma_f32_16x16x32_bf16 v[68:71], v[164:167], v[212:215], v[68:71]
	v_mfma_f32_16x16x32_bf16 v[64:67], v[172:175], v[212:215], v[64:67]
	s_barrier
; #define PG8_STAGE(bufoff, gbase, voff) do { _Pragma("unroll") for (int _i = 0; _i < 2; ++_i) \
;         __builtin_amdgcn_global_load_lds((const unsigned*)((const char*)(gbase) + (voff)[_i]), (LAS unsigned*)(lds + (bufoff) + ldsw + _i * 8192), 16, 0, 0); } while (0)
; #define PG8_LDA(dst, b, h) do { _Pragma("unroll") for (int m = 0; m < 4; ++m) _Pragma("unroll") for (int k = 0; k < 2; ++k) dst[m][k] = *(const LAS bf16x8*)(lds + PG8_SA(b, h) + aoff + m * 2048 + k * 1024); } while (0)
; #define PG8_MMA(ai, bj, At, Bt) do { __builtin_amdgcn_s_setprio(1); _Pragma("unroll") for (int m = 0; m < 4; ++m) _Pragma("unroll") for (int n = 0; n < 2; ++n) _Pragma("unroll") for (int k = 0; k < 2; ++k) \
;         acc[ai][bj][m][n] = __builtin_amdgcn_mfma_f32_16x16x32_bf16(Bt[n][k], At[m][k], acc[ai][bj][m][n], 0, 0, 0); __builtin_amdgcn_s_setprio(0); } while (0)
; #define PG8_WAIT_V(n) asm volatile("s_waitcnt vmcnt(" #n ")" ::: "memory")
; #define PG8_WAIT_L(n) asm volatile("s_waitcnt lgkmcnt(" #n ")" ::: "memory")
; #define PG8_BAR __builtin_amdgcn_s_barrier()
; #define PG8_SCHED __builtin_amdgcn_sched_barrier(0)
; template <class Epi, class Sched>
; DI void gemm_phase(LAS unsigned char* lds, const int wv, const int lda, const int ldb, const Sched& S, const Epi& E) {
;     ...
;             PG8_LDA(At, 1, 1); PG8_STAGE(PG8_SB(1, 0), b3, voffB); PG8_STAGE(PG8_SB(1, 1), b3 + hstepB, voffB); PG8_STAGE(PG8_SA(1, 0), a3, voffA);
;             PG8_WAIT_V(8); PG8_WAIT_L(0); PG8_BAR; PG8_MMA(1, 0, At, B0); PG8_MMA(1, 1, At, B1); PG8_BAR; PG8_SCHED;
;         }
	s_add_i32 s34, s51, s38
	v_lshl_add_u64 v[142:143], v[142:143], 0, s[28:29]
	s_mov_b32 m0, s34
	ds_read_b128 v[176:179], v147 offset:49152
	ds_read_b128 v[180:183], v147 offset:50176
	ds_read_b128 v[188:191], v147 offset:51200
	ds_read_b128 v[196:199], v147 offset:52224
	ds_read_b128 v[200:203], v147 offset:53248
	ds_read_b128 v[204:207], v147 offset:54272
	ds_read_b128 v[208:211], v147 offset:55296
	ds_read_b128 v[212:215], v147 offset:56320
	global_load_lds_dwordx4 v[142:143], off
	s_add_i32 m0, s34, 0x2000
	s_add_u32 s30, s30, 0x80080
	v_lshl_add_u64 v[142:143], v[216:217], 0, s[28:29]
	s_addc_u32 s31, s31, 0
	s_add_i32 s34, s52, s38
	global_load_lds_dwordx4 v[142:143], off
	v_lshl_add_u64 v[142:143], s[30:31], 0, v[184:185]
	s_mov_b32 m0, s34
	s_nop 0
	global_load_lds_dwordx4 v[142:143], off
	v_lshl_add_u64 v[142:143], s[30:31], 0, v[132:133]
	s_add_i32 m0, s34, 0x2000
	s_nop 0
	global_load_lds_dwordx4 v[142:143], off
	v_lshl_add_u64 v[142:143], v[218:219], 0, s[28:29]
	s_mov_b32 m0, s43
	s_nop 0
	global_load_lds_dwordx4 v[142:143], off
	v_lshl_add_u64 v[142:143], v[220:221], 0, s[28:29]
	s_mov_b32 m0, s44
	s_nop 0
	global_load_lds_dwordx4 v[142:143], off
	s_waitcnt vmcnt(8) lgkmcnt(0)
	s_barrier
	v_mfma_f32_16x16x32_bf16 v[60:63], v[138:141], v[176:179], v[60:63]
	v_mfma_f32_16x16x32_bf16 v[56:59], v[152:155], v[176:179], v[56:59]
	v_mfma_f32_16x16x32_bf16 v[44:47], v[138:141], v[188:191], v[44:47]
	v_mfma_f32_16x16x32_bf16 v[40:43], v[152:155], v[188:191], v[40:43]
	v_mfma_f32_16x16x32_bf16 v[28:31], v[138:141], v[200:203], v[28:31]
	v_mfma_f32_16x16x32_bf16 v[24:27], v[152:155], v[200:203], v[24:27]
	v_mfma_f32_16x16x32_bf16 v[12:15], v[138:141], v[208:211], v[12:15]
	v_mfma_f32_16x16x32_bf16 v[8:11], v[152:155], v[208:211], v[8:11]
	v_mfma_f32_16x16x32_bf16 v[60:63], v[148:151], v[180:183], v[60:63]
	v_mfma_f32_16x16x32_bf16 v[56:59], v[156:159], v[180:183], v[56:59]
	v_mfma_f32_16x16x32_bf16 v[44:47], v[148:151], v[196:199], v[44:47]
	v_mfma_f32_16x16x32_bf16 v[40:43], v[156:159], v[196:199], v[40:43]
	v_mfma_f32_16x16x32_bf16 v[28:31], v[148:151], v[204:207], v[28:31]
	v_mfma_f32_16x16x32_bf16 v[24:27], v[156:159], v[204:207], v[24:27]
	v_mfma_f32_16x16x32_bf16 v[12:15], v[148:151], v[212:215], v[12:15]
	v_mfma_f32_16x16x32_bf16 v[8:11], v[156:159], v[212:215], v[8:11]
	v_mfma_f32_16x16x32_bf16 v[52:55], v[160:163], v[176:179], v[52:55]
	v_mfma_f32_16x16x32_bf16 v[48:51], v[168:171], v[176:179], v[48:51]
	v_mfma_f32_16x16x32_bf16 v[36:39], v[160:163], v[188:191], v[36:39]
	v_mfma_f32_16x16x32_bf16 v[32:35], v[168:171], v[188:191], v[32:35]
	v_mfma_f32_16x16x32_bf16 v[20:23], v[160:163], v[200:203], v[20:23]
	v_mfma_f32_16x16x32_bf16 v[16:19], v[168:171], v[200:203], v[16:19]
	v_mfma_f32_16x16x32_bf16 v[4:7], v[160:163], v[208:211], v[4:7]
	v_mfma_f32_16x16x32_bf16 v[0:3], v[168:171], v[208:211], v[0:3]
	v_mfma_f32_16x16x32_bf16 v[52:55], v[164:167], v[180:183], v[52:55]
	v_mfma_f32_16x16x32_bf16 v[48:51], v[172:175], v[180:183], v[48:51]
	v_mfma_f32_16x16x32_bf16 v[36:39], v[164:167], v[196:199], v[36:39]
	v_mfma_f32_16x16x32_bf16 v[32:35], v[172:175], v[196:199], v[32:35]
	v_mfma_f32_16x16x32_bf16 v[20:23], v[164:167], v[204:207], v[20:23]
	v_mfma_f32_16x16x32_bf16 v[16:19], v[172:175], v[204:207], v[16:19]
	v_mfma_f32_16x16x32_bf16 v[4:7], v[164:167], v[212:215], v[4:7]
	v_mfma_f32_16x16x32_bf16 v[0:3], v[172:175], v[212:215], v[0:3]
	s_barrier
	s_add_i32 s50, s50, 2
	s_add_u32 s26, s26, 0x100
	s_addc_u32 s27, s27, 0
	s_add_u32 s48, s48, 0x100
	s_addc_u32 s49, s49, 0

;     DI bool next(int i, Unit& u) const { const long L = (long)i * G + c; if (L >= T.nwg) return false; T.map((int)L, u.pm, u.pn); u.seg = 0; return true; }
;     DI bool next(int i, Unit& u) const { const int ti = i / 3; const long L = (long)ti * G + c; if (L >= T.nwg) return false; T.map((int)L, u.pm, u.pn); u.seg = i - 3 * ti; return true; }
;     DI const char* aptr(const Unit& u) const { return A + (size_t)u.pm * ta + (size_t)kofs(u.seg) * 2; }
;     DI const char* bptr(const Unit& u) const { return B + (size_t)u.pn * tb + (size_t)kofs(u.seg) * 2; }
; #define PG8_STAGE(bufoff, gbase, voff) do { _Pragma("unroll") for (int _i = 0; _i < 2; ++_i) \
;         __builtin_amdgcn_global_load_lds((const unsigned*)((const char*)(gbase) + (voff)[_i]), (LAS unsigned*)(lds + (bufoff) + ldsw + _i * 8192), 16, 0, 0); } while (0)
; #define PG8_LDA(dst, b, h) do { _Pragma("unroll") for (int m = 0; m < 4; ++m) _Pragma("unroll") for (int k = 0; k < 2; ++k) dst[m][k] = *(const LAS bf16x8*)(lds + PG8_SA(b, h) + aoff + m * 2048 + k * 1024); } while (0)
; #define PG8_WAIT_V(n) asm volatile("s_waitcnt vmcnt(" #n ")" ::: "memory")
; #define PG8_WAIT_L(n) asm volatile("s_waitcnt lgkmcnt(" #n ")" ::: "memory")
; template <class Epi, class Sched>
; DI void gemm_phase(LAS unsigned char* lds, const int wv, const int lda, const int ldb, const Sched& S, const Epi& E) {
;     ...
;         const bool has_next = S.next(ui + 1, nxt);
;         const char* nA = has_next ? S.aptr(nxt) : cA; const char* nB = has_next ? S.bptr(nxt) : cB;
;         for (int t = 0; t < nt; t += 2) {
;             const bool last = (t == nt - 2);
;             const char* a1 = cA + (size_t)(t + 1) * kstep;
;             const char* a2 = last ? nA : cA + (size_t)(t + 2) * kstep; const char* b2 = last ? nB : cB + (size_t)(t + 2) * kstep;
;             const char* a3 = a2 + kstep; const char* b3 = b2 + kstep;
;             PG8_LDB(B0, 0, 0); PG8_LDB(B1, 0, 1); PG8_SCHED; PG8_LDA(At, 0, 0); PG8_STAGE(PG8_SA(1, 1), a1 + hstepA, voffA);
;             PG8_WAIT_V(8); PG8_WAIT_L(0); PG8_BAR; PG8_MMA(0, 0, At, B0); PG8_MMA(0, 1, At, B1); PG8_BAR; PG8_SCHED;
;             PG8_LDA(At, 0, 1); PG8_STAGE(PG8_SB(0, 0), b2, voffB); PG8_STAGE(PG8_SB(0, 1), b2 + hstepB, voffB); PG8_STAGE(PG8_SA(0, 0), a2, voffA);
;             PG8_WAIT_V(8); PG8_WAIT_L(0); PG8_BAR; PG8_MMA(1, 0, At, B0); PG8_MMA(1, 1, At, B1); PG8_BAR; PG8_SCHED;
.LBB0_1476:
	s_ashr_i32 s23, s22, 31
	s_lshl_b64 s[0:1], s[22:23], 22
	s_add_u32 s24, s33, s0
	s_addc_u32 s25, s40, s1
	s_and_b64 s[0:1], s[6:7], exec
	s_cselect_b32 s0, s25, s35
	s_cselect_b32 s1, s24, s34
	s_ashr_i32 s11, s10, 31
	s_lshl_b64 s[26:27], s[10:11], 22
	s_add_u32 s26, s41, s26
	s_addc_u32 s27, s42, s27
	s_and_b64 s[38:39], s[6:7], exec
	s_cselect_b32 s11, s27, s37
	s_cselect_b32 s19, s26, s36
	s_add_u32 s34, s34, 0x200080
	s_addc_u32 s35, s35, 0
	s_add_u32 s23, s36, 0x100
	s_addc_u32 s54, s37, 0
	s_mov_b32 s55, -2
	s_waitcnt lgkmcnt(0)
	s_add_u32 s36, s34, 0xffe00080
	s_addc_u32 s37, s35, -1
	s_add_i32 s56, 0, 0x10000
	s_cmpk_eq_i32 s55, 0x7c
	s_cselect_b32 s39, s0, s37
	s_cselect_b32 s38, s1, s36
	s_cselect_b32 s37, s11, s54
	s_cselect_b32 s36, s19, s23
	s_add_i32 s58, 0, 0x14000
	v_add_u32_e32 v150, s56, v155
	v_add_u32_e32 v172, s58, v155
	ds_read_b128 v[128:131], v150
	ds_read_b128 v[142:145], v150 offset:1024
	ds_read_b128 v[146:149], v150 offset:2048
	ds_read_b128 v[150:153], v150 offset:3072
	ds_read_b128 v[160:163], v172
	ds_read_b128 v[164:167], v172 offset:1024
	ds_read_b128 v[168:171], v172 offset:2048
	ds_read_b128 v[172:175], v172 offset:3072
	v_lshl_add_u64 v[216:217], s[34:35], 0, v[138:139]
	s_add_i32 m0, s31, 0xc000
	ds_read_b128 v[176:179], v159
	ds_read_b128 v[180:183], v159 offset:1024
	ds_read_b128 v[188:191], v159 offset:2048
	ds_read_b128 v[196:199], v159 offset:3072
	ds_read_b128 v[200:203], v159 offset:4096
	ds_read_b128 v[204:207], v159 offset:5120
	ds_read_b128 v[208:211], v159 offset:6144
	ds_read_b128 v[212:215], v159 offset:7168
	global_load_lds_dwordx4 v[216:217], off
	v_lshl_add_u64 v[216:217], s[34:35], 0, v[140:141]
	s_add_i32 m0, s31, 0xe000
	s_nop 0
	global_load_lds_dwordx4 v[216:217], off
	s_waitcnt vmcnt(8) lgkmcnt(0)
	s_barrier
	v_mfma_f32_16x16x32_bf16 v[124:127], v[128:131], v[176:179], 0
	v_mfma_f32_16x16x32_bf16 v[120:123], v[146:149], v[176:179], 0
	v_mfma_f32_16x16x32_bf16 v[108:111], v[128:131], v[188:191], 0
	v_mfma_f32_16x16x32_bf16 v[104:107], v[146:149], v[188:191], 0
	v_mfma_f32_16x16x32_bf16 v[96:99], v[128:131], v[200:203], 0
	v_mfma_f32_16x16x32_bf16 v[88:91], v[146:149], v[200:203], 0
	v_mfma_f32_16x16x32_bf16 v[80:83], v[128:131], v[208:211], 0
	v_mfma_f32_16x16x32_bf16 v[72:75], v[146:149], v[208:211], 0
	v_mfma_f32_16x16x32_bf16 v[124:127], v[142:145], v[180:183], v[124:127]
	v_mfma_f32_16x16x32_bf16 v[120:123], v[150:153], v[180:183], v[120:123]
	v_mfma_f32_16x16x32_bf16 v[108:111], v[142:145], v[196:199], v[108:111]
	v_mfma_f32_16x16x32_bf16 v[104:107], v[150:153], v[196:199], v[104:107]
	v_mfma_f32_16x16x32_bf16 v[96:99], v[142:145], v[204:207], v[96:99]
	v_mfma_f32_16x16x32_bf16 v[88:91], v[150:153], v[204:207], v[88:91]
	v_mfma_f32_16x16x32_bf16 v[80:83], v[142:145], v[212:215], v[80:83]
	v_mfma_f32_16x16x32_bf16 v[72:75], v[150:153], v[212:215], v[72:75]
	v_mfma_f32_16x16x32_bf16 v[116:119], v[160:163], v[176:179], 0
	v_mfma_f32_16x16x32_bf16 v[112:115], v[168:171], v[176:179], 0
	v_mfma_f32_16x16x32_bf16 v[100:103], v[160:163], v[188:191], 0
	v_mfma_f32_16x16x32_bf16 v[92:95], v[168:171], v[188:191], 0
	v_mfma_f32_16x16x32_bf16 v[84:87], v[160:163], v[200:203], 0
	v_mfma_f32_16x16x32_bf16 v[76:79], v[168:171], v[200:203], 0
	v_mfma_f32_16x16x32_bf16 v[68:71], v[160:163], v[208:211], 0
	v_mfma_f32_16x16x32_bf16 v[64:67], v[168:171], v[208:211], 0
	v_mfma_f32_16x16x32_bf16 v[116:119], v[164:167], v[180:183], v[116:119]
	v_mfma_f32_16x16x32_bf16 v[112:115], v[172:175], v[180:183], v[112:115]
	v_mfma_f32_16x16x32_bf16 v[100:103], v[164:167], v[196:199], v[100:103]
	v_mfma_f32_16x16x32_bf16 v[92:95], v[172:175], v[196:199], v[92:95]
	v_mfma_f32_16x16x32_bf16 v[84:87], v[164:167], v[204:207], v[84:87]
	v_mfma_f32_16x16x32_bf16 v[76:79], v[172:175], v[204:207], v[76:79]
	v_mfma_f32_16x16x32_bf16 v[68:71], v[164:167], v[212:215], v[68:71]
	v_mfma_f32_16x16x32_bf16 v[64:67], v[172:175], v[212:215], v[64:67]
	s_barrier
	s_add_i32 s56, s56, s43
	v_lshl_add_u64 v[216:217], s[36:37], 0, v[184:185]
	s_mov_b32 m0, s56
	ds_read_b128 v[176:179], v159 offset:16384
	ds_read_b128 v[180:183], v159 offset:17408
	ds_read_b128 v[188:191], v159 offset:18432
	ds_read_b128 v[196:199], v159 offset:19456
	ds_read_b128 v[200:203], v159 offset:20480
	ds_read_b128 v[204:207], v159 offset:21504
	ds_read_b128 v[208:211], v159 offset:22528
	ds_read_b128 v[212:215], v159 offset:23552
	global_load_lds_dwordx4 v[216:217], off
	s_add_i32 m0, s56, 0x2000
	s_add_u32 s56, s36, 0x200000
	v_lshl_add_u64 v[218:219], s[36:37], 0, v[136:137]
	s_addc_u32 s57, s37, 0
	s_add_i32 s58, s58, s43
	global_load_lds_dwordx4 v[218:219], off
	v_lshl_add_u64 v[220:221], s[56:57], 0, v[184:185]
	s_mov_b32 m0, s58
	v_lshl_add_u64 v[222:223], s[38:39], 0, v[134:135]
	global_load_lds_dwordx4 v[220:221], off
	v_lshl_add_u64 v[220:221], s[56:57], 0, v[136:137]
	s_add_i32 m0, s58, 0x2000
	s_nop 0
	global_load_lds_dwordx4 v[220:221], off
	v_lshl_add_u64 v[220:221], s[38:39], 0, v[132:133]
	s_mov_b32 m0, s31
	s_nop 0
	global_load_lds_dwordx4 v[220:221], off
	s_mov_b32 m0, s44
	s_nop 0
	global_load_lds_dwordx4 v[222:223], off
	s_waitcnt vmcnt(8) lgkmcnt(0)
	s_barrier
; #define PG8_STAGE(bufoff, gbase, voff) do { _Pragma("unroll") for (int _i = 0; _i < 2; ++_i) \
;         __builtin_amdgcn_global_load_lds((const unsigned*)((const char*)(gbase) + (voff)[_i]), (LAS unsigned*)(lds + (bufoff) + ldsw + _i * 8192), 16, 0, 0); } while (0)
; #define PG8_LDA(dst, b, h) do { _Pragma("unroll") for (int m = 0; m < 4; ++m) _Pragma("unroll") for (int k = 0; k < 2; ++k) dst[m][k] = *(const LAS bf16x8*)(lds + PG8_SA(b, h) + aoff + m * 2048 + k * 1024); } while (0)
; #define PG8_LDB(dst, b, h) do { _Pragma("unroll") for (int n = 0; n < 2; ++n) _Pragma("unroll") for (int k = 0; k < 2; ++k) dst[n][k] = *(const LAS bf16x8*)(lds + PG8_SB(b, h) + boff + n * 2048 + k * 1024); } while (0)
; #define PG8_MMA(ai, bj, At, Bt) do { __builtin_amdgcn_s_setprio(1); _Pragma("unroll") for (int m = 0; m < 4; ++m) _Pragma("unroll") for (int n = 0; n < 2; ++n) _Pragma("unroll") for (int k = 0; k < 2; ++k) \
;         acc[ai][bj][m][n] = __builtin_amdgcn_mfma_f32_16x16x32_bf16(Bt[n][k], At[m][k], acc[ai][bj][m][n], 0, 0, 0); __builtin_amdgcn_s_setprio(0); } while (0)
; #define PG8_WAIT_V(n) asm volatile("s_waitcnt vmcnt(" #n ")" ::: "memory")
; #define PG8_WAIT_L(n) asm volatile("s_waitcnt lgkmcnt(" #n ")" ::: "memory")
; #define PG8_BAR __builtin_amdgcn_s_barrier()
; #define PG8_SCHED __builtin_amdgcn_sched_barrier(0)
; template <class Epi, class Sched>
; DI void gemm_phase(LAS unsigned char* lds, const int wv, const int lda, const int ldb, const Sched& S, const Epi& E) {
;     ...
;             PG8_WAIT_V(8); PG8_WAIT_L(0); PG8_BAR; PG8_MMA(1, 0, At, B0); PG8_MMA(1, 1, At, B1); PG8_BAR; PG8_SCHED;
;             PG8_LDB(B0, 1, 0); PG8_LDB(B1, 1, 1); PG8_SCHED; PG8_LDA(At, 1, 0); PG8_STAGE(PG8_SA(0, 1), a2 + hstepA, voffA);
;             PG8_WAIT_V(8); PG8_WAIT_L(0); PG8_BAR; PG8_MMA(0, 0, At, B0); PG8_MMA(0, 1, At, B1); PG8_BAR; PG8_SCHED;
	v_mfma_f32_16x16x32_bf16 v[60:63], v[128:131], v[176:179], 0
	v_mfma_f32_16x16x32_bf16 v[56:59], v[146:149], v[176:179], 0
	v_mfma_f32_16x16x32_bf16 v[48:51], v[128:131], v[188:191], 0
	v_mfma_f32_16x16x32_bf16 v[40:43], v[146:149], v[188:191], 0
	v_mfma_f32_16x16x32_bf16 v[32:35], v[128:131], v[200:203], 0
	v_mfma_f32_16x16x32_bf16 v[24:27], v[146:149], v[200:203], 0
	v_mfma_f32_16x16x32_bf16 v[16:19], v[128:131], v[208:211], 0
	v_mfma_f32_16x16x32_bf16 v[8:11], v[146:149], v[208:211], 0
	v_mfma_f32_16x16x32_bf16 v[60:63], v[142:145], v[180:183], v[60:63]
	v_mfma_f32_16x16x32_bf16 v[56:59], v[150:153], v[180:183], v[56:59]
	v_mfma_f32_16x16x32_bf16 v[48:51], v[142:145], v[196:199], v[48:51]
	v_mfma_f32_16x16x32_bf16 v[40:43], v[150:153], v[196:199], v[40:43]
	v_mfma_f32_16x16x32_bf16 v[32:35], v[142:145], v[204:207], v[32:35]
	v_mfma_f32_16x16x32_bf16 v[24:27], v[150:153], v[204:207], v[24:27]
	v_mfma_f32_16x16x32_bf16 v[16:19], v[142:145], v[212:215], v[16:19]
	v_mfma_f32_16x16x32_bf16 v[8:11], v[150:153], v[212:215], v[8:11]
	v_mfma_f32_16x16x32_bf16 v[52:55], v[160:163], v[176:179], 0
	v_mfma_f32_16x16x32_bf16 v[44:47], v[168:171], v[176:179], 0
	v_mfma_f32_16x16x32_bf16 v[36:39], v[160:163], v[188:191], 0
	v_mfma_f32_16x16x32_bf16 v[28:31], v[168:171], v[188:191], 0
	v_mfma_f32_16x16x32_bf16 v[20:23], v[160:163], v[200:203], 0
	v_mfma_f32_16x16x32_bf16 v[12:15], v[168:171], v[200:203], 0
	v_mfma_f32_16x16x32_bf16 v[4:7], v[160:163], v[208:211], 0
	v_mfma_f32_16x16x32_bf16 v[0:3], v[168:171], v[208:211], 0
	v_mfma_f32_16x16x32_bf16 v[52:55], v[164:167], v[180:183], v[52:55]
	v_mfma_f32_16x16x32_bf16 v[44:47], v[172:175], v[180:183], v[44:47]
	v_mfma_f32_16x16x32_bf16 v[36:39], v[164:167], v[196:199], v[36:39]
	v_mfma_f32_16x16x32_bf16 v[28:31], v[172:175], v[196:199], v[28:31]
	v_mfma_f32_16x16x32_bf16 v[20:23], v[164:167], v[204:207], v[20:23]
	v_mfma_f32_16x16x32_bf16 v[12:15], v[172:175], v[204:207], v[12:15]
	v_mfma_f32_16x16x32_bf16 v[4:7], v[164:167], v[212:215], v[4:7]
	v_mfma_f32_16x16x32_bf16 v[0:3], v[172:175], v[212:215], v[0:3]
	s_barrier
	s_add_i32 s56, 0, 0x18000
	s_add_i32 s57, 0, 0x1c000
	v_add_u32_e32 v150, s56, v155
	v_add_u32_e32 v172, s57, v155
	ds_read_b128 v[128:131], v150
	ds_read_b128 v[142:145], v150 offset:1024
	ds_read_b128 v[146:149], v150 offset:2048
	ds_read_b128 v[150:153], v150 offset:3072
	ds_read_b128 v[160:163], v172
	ds_read_b128 v[164:167], v172 offset:1024
	ds_read_b128 v[168:171], v172 offset:2048
	ds_read_b128 v[172:175], v172 offset:3072
	s_add_u32 s38, s38, 0x200000
	s_addc_u32 s39, s39, 0
	s_mov_b32 m0, s45
	v_lshl_add_u64 v[234:235], s[38:39], 0, v[132:133]
	ds_read_b128 v[176:179], v159 offset:32768
	ds_read_b128 v[180:183], v159 offset:33792
	ds_read_b128 v[188:191], v159 offset:34816
	ds_read_b128 v[196:199], v159 offset:35840
	ds_read_b128 v[200:203], v159 offset:36864
	ds_read_b128 v[204:207], v159 offset:37888
	ds_read_b128 v[208:211], v159 offset:38912
	ds_read_b128 v[212:215], v159 offset:39936
	global_load_lds_dwordx4 v[234:235], off
	v_lshl_add_u64 v[234:235], s[38:39], 0, v[134:135]
	s_mov_b32 m0, s46
	s_nop 0
	global_load_lds_dwordx4 v[234:235], off
	s_waitcnt vmcnt(8) lgkmcnt(0)
	s_barrier
	v_mfma_f32_16x16x32_bf16 v[124:127], v[128:131], v[176:179], v[124:127]
	v_mfma_f32_16x16x32_bf16 v[120:123], v[146:149], v[176:179], v[120:123]
	v_mfma_f32_16x16x32_bf16 v[108:111], v[128:131], v[188:191], v[108:111]
	v_mfma_f32_16x16x32_bf16 v[104:107], v[146:149], v[188:191], v[104:107]
	v_mfma_f32_16x16x32_bf16 v[96:99], v[128:131], v[200:203], v[96:99]
	v_mfma_f32_16x16x32_bf16 v[88:91], v[146:149], v[200:203], v[88:91]
	v_mfma_f32_16x16x32_bf16 v[80:83], v[128:131], v[208:211], v[80:83]
	v_mfma_f32_16x16x32_bf16 v[72:75], v[146:149], v[208:211], v[72:75]
	v_mfma_f32_16x16x32_bf16 v[124:127], v[142:145], v[180:183], v[124:127]
	v_mfma_f32_16x16x32_bf16 v[120:123], v[150:153], v[180:183], v[120:123]
	v_mfma_f32_16x16x32_bf16 v[108:111], v[142:145], v[196:199], v[108:111]
	v_mfma_f32_16x16x32_bf16 v[104:107], v[150:153], v[196:199], v[104:107]
	v_mfma_f32_16x16x32_bf16 v[96:99], v[142:145], v[204:207], v[96:99]
	v_mfma_f32_16x16x32_bf16 v[88:91], v[150:153], v[204:207], v[88:91]
	v_mfma_f32_16x16x32_bf16 v[80:83], v[142:145], v[212:215], v[80:83]
	v_mfma_f32_16x16x32_bf16 v[72:75], v[150:153], v[212:215], v[72:75]
	v_mfma_f32_16x16x32_bf16 v[116:119], v[160:163], v[176:179], v[116:119]
	v_mfma_f32_16x16x32_bf16 v[112:115], v[168:171], v[176:179], v[112:115]
	v_mfma_f32_16x16x32_bf16 v[100:103], v[160:163], v[188:191], v[100:103]
	v_mfma_f32_16x16x32_bf16 v[92:95], v[168:171], v[188:191], v[92:95]
	v_mfma_f32_16x16x32_bf16 v[84:87], v[160:163], v[200:203], v[84:87]
	v_mfma_f32_16x16x32_bf16 v[76:79], v[168:171], v[200:203], v[76:79]
	v_mfma_f32_16x16x32_bf16 v[68:71], v[160:163], v[208:211], v[68:71]
	v_mfma_f32_16x16x32_bf16 v[64:67], v[168:171], v[208:211], v[64:67]
	v_mfma_f32_16x16x32_bf16 v[116:119], v[164:167], v[180:183], v[116:119]
	v_mfma_f32_16x16x32_bf16 v[112:115], v[172:175], v[180:183], v[112:115]
	v_mfma_f32_16x16x32_bf16 v[100:103], v[164:167], v[196:199], v[100:103]
	v_mfma_f32_16x16x32_bf16 v[92:95], v[172:175], v[196:199], v[92:95]
	v_mfma_f32_16x16x32_bf16 v[84:87], v[164:167], v[204:207], v[84:87]
	v_mfma_f32_16x16x32_bf16 v[76:79], v[172:175], v[204:207], v[76:79]
	v_mfma_f32_16x16x32_bf16 v[68:71], v[164:167], v[212:215], v[68:71]
	v_mfma_f32_16x16x32_bf16 v[64:67], v[172:175], v[212:215], v[64:67]
	s_barrier
; #define PG8_STAGE(bufoff, gbase, voff) do { _Pragma("unroll") for (int _i = 0; _i < 2; ++_i) \
;         __builtin_amdgcn_global_load_lds((const unsigned*)((const char*)(gbase) + (voff)[_i]), (LAS unsigned*)(lds + (bufoff) + ldsw + _i * 8192), 16, 0, 0); } while (0)
; #define PG8_LDA(dst, b, h) do { _Pragma("unroll") for (int m = 0; m < 4; ++m) _Pragma("unroll") for (int k = 0; k < 2; ++k) dst[m][k] = *(const LAS bf16x8*)(lds + PG8_SA(b, h) + aoff + m * 2048 + k * 1024); } while (0)
; #define PG8_MMA(ai, bj, At, Bt) do { __builtin_amdgcn_s_setprio(1); _Pragma("unroll") for (int m = 0; m < 4; ++m) _Pragma("unroll") for (int n = 0; n < 2; ++n) _Pragma("unroll") for (int k = 0; k < 2; ++k) \
;         acc[ai][bj][m][n] = __builtin_amdgcn_mfma_f32_16x16x32_bf16(Bt[n][k], At[m][k], acc[ai][bj][m][n], 0, 0, 0); __builtin_amdgcn_s_setprio(0); } while (0)
; #define PG8_WAIT_V(n) asm volatile("s_waitcnt vmcnt(" #n ")" ::: "memory")
; #define PG8_WAIT_L(n) asm volatile("s_waitcnt lgkmcnt(" #n ")" ::: "memory")
; #define PG8_BAR __builtin_amdgcn_s_barrier()
; #define PG8_SCHED __builtin_amdgcn_sched_barrier(0)
; template <class Epi, class Sched>
; DI void gemm_phase(LAS unsigned char* lds, const int wv, const int lda, const int ldb, const Sched& S, const Epi& E) {
;     ...
;             PG8_LDA(At, 1, 1); PG8_STAGE(PG8_SB(1, 0), b3, voffB); PG8_STAGE(PG8_SB(1, 1), b3 + hstepB, voffB); PG8_STAGE(PG8_SA(1, 0), a3, voffA);
;             PG8_WAIT_V(8); PG8_WAIT_L(0); PG8_BAR; PG8_MMA(1, 0, At, B0); PG8_MMA(1, 1, At, B1); PG8_BAR; PG8_SCHED;
;         }
	s_add_i32 s38, s56, s43
	v_lshl_add_u64 v[216:217], v[216:217], 0, s[28:29]
	s_mov_b32 m0, s38
	ds_read_b128 v[176:179], v159 offset:49152
	ds_read_b128 v[180:183], v159 offset:50176
	ds_read_b128 v[188:191], v159 offset:51200
	ds_read_b128 v[196:199], v159 offset:52224
	ds_read_b128 v[200:203], v159 offset:53248
	ds_read_b128 v[204:207], v159 offset:54272
	ds_read_b128 v[208:211], v159 offset:55296
	ds_read_b128 v[212:215], v159 offset:56320
	global_load_lds_dwordx4 v[216:217], off
	s_add_i32 m0, s38, 0x2000
	s_add_u32 s36, s36, 0x200080
	v_lshl_add_u64 v[216:217], v[218:219], 0, s[28:29]
	s_addc_u32 s37, s37, 0
	s_add_i32 s38, s57, s43
	global_load_lds_dwordx4 v[216:217], off
	v_lshl_add_u64 v[216:217], s[36:37], 0, v[184:185]
	s_mov_b32 m0, s38
	s_nop 0
	global_load_lds_dwordx4 v[216:217], off
	v_lshl_add_u64 v[216:217], s[36:37], 0, v[136:137]
	s_add_i32 m0, s38, 0x2000
	s_nop 0
	global_load_lds_dwordx4 v[216:217], off
	v_lshl_add_u64 v[216:217], v[220:221], 0, s[28:29]
	s_mov_b32 m0, s47
	s_nop 0
	global_load_lds_dwordx4 v[216:217], off
	v_lshl_add_u64 v[216:217], v[222:223], 0, s[28:29]
	s_mov_b32 m0, s48
	s_nop 0
	global_load_lds_dwordx4 v[216:217], off
	s_waitcnt vmcnt(8) lgkmcnt(0)
	s_barrier
	v_mfma_f32_16x16x32_bf16 v[60:63], v[128:131], v[176:179], v[60:63]
	v_mfma_f32_16x16x32_bf16 v[56:59], v[146:149], v[176:179], v[56:59]
	v_mfma_f32_16x16x32_bf16 v[48:51], v[128:131], v[188:191], v[48:51]
	v_mfma_f32_16x16x32_bf16 v[40:43], v[146:149], v[188:191], v[40:43]
	v_mfma_f32_16x16x32_bf16 v[32:35], v[128:131], v[200:203], v[32:35]
	v_mfma_f32_16x16x32_bf16 v[24:27], v[146:149], v[200:203], v[24:27]
	v_mfma_f32_16x16x32_bf16 v[16:19], v[128:131], v[208:211], v[16:19]
	v_mfma_f32_16x16x32_bf16 v[8:11], v[146:149], v[208:211], v[8:11]
	v_mfma_f32_16x16x32_bf16 v[60:63], v[142:145], v[180:183], v[60:63]
	v_mfma_f32_16x16x32_bf16 v[56:59], v[150:153], v[180:183], v[56:59]
	v_mfma_f32_16x16x32_bf16 v[48:51], v[142:145], v[196:199], v[48:51]
	v_mfma_f32_16x16x32_bf16 v[40:43], v[150:153], v[196:199], v[40:43]
	v_mfma_f32_16x16x32_bf16 v[32:35], v[142:145], v[204:207], v[32:35]
	v_mfma_f32_16x16x32_bf16 v[24:27], v[150:153], v[204:207], v[24:27]
	v_mfma_f32_16x16x32_bf16 v[16:19], v[142:145], v[212:215], v[16:19]
	v_mfma_f32_16x16x32_bf16 v[8:11], v[150:153], v[212:215], v[8:11]
	v_mfma_f32_16x16x32_bf16 v[52:55], v[160:163], v[176:179], v[52:55]
	v_mfma_f32_16x16x32_bf16 v[44:47], v[168:171], v[176:179], v[44:47]
	v_mfma_f32_16x16x32_bf16 v[36:39], v[160:163], v[188:191], v[36:39]
	v_mfma_f32_16x16x32_bf16 v[28:31], v[168:171], v[188:191], v[28:31]
	v_mfma_f32_16x16x32_bf16 v[20:23], v[160:163], v[200:203], v[20:23]
	v_mfma_f32_16x16x32_bf16 v[12:15], v[168:171], v[200:203], v[12:15]
	v_mfma_f32_16x16x32_bf16 v[4:7], v[160:163], v[208:211], v[4:7]
	v_mfma_f32_16x16x32_bf16 v[0:3], v[168:171], v[208:211], v[0:3]
	v_mfma_f32_16x16x32_bf16 v[52:55], v[164:167], v[180:183], v[52:55]
	v_mfma_f32_16x16x32_bf16 v[44:47], v[172:175], v[180:183], v[44:47]
	v_mfma_f32_16x16x32_bf16 v[36:39], v[164:167], v[196:199], v[36:39]
	v_mfma_f32_16x16x32_bf16 v[28:31], v[172:175], v[196:199], v[28:31]
	v_mfma_f32_16x16x32_bf16 v[20:23], v[164:167], v[204:207], v[20:23]
	v_mfma_f32_16x16x32_bf16 v[12:15], v[172:175], v[204:207], v[12:15]
	v_mfma_f32_16x16x32_bf16 v[4:7], v[164:167], v[212:215], v[4:7]
	v_mfma_f32_16x16x32_bf16 v[0:3], v[172:175], v[212:215], v[0:3]
	s_barrier
	s_add_i32 s55, s55, 2
	s_add_u32 s34, s34, 0x100
	s_addc_u32 s35, s35, 0
	s_add_u32 s23, s23, 0x100
	s_addc_u32 s54, s54, 0
